# batched the serialized global loads in the layer-1 weight-conversion loop (16 loads per tile issued together) + hand-written norm_mod fast paths (4 tokens per wave, loads batched)
# speedup vs baseline: 1.1001x; 1.0438x over previous
.LBB0_248:
	v_add_u32_e32 v70, s17, v1
	v_add_u32_e32 v67, s17, v14
	v_add_u32_e32 v66, s17, v15
	v_add_u32_e32 v65, s17, v16
	v_add_u32_e32 v60, s17, v17
	v_add_u32_e32 v59, s17, v18
	v_add_u32_e32 v54, s17, v19
	v_add_u32_e32 v53, s17, v20
	v_add_u32_e32 v48, s17, v21
	v_add_u32_e32 v47, s17, v22
	v_add_u32_e32 v42, s17, v23
	v_add_u32_e32 v41, s17, v24
	v_add_u32_e32 v36, s17, v25
	v_add_u32_e32 v35, s17, v26
	v_add_u32_e32 v30, s17, v27
	v_add_u32_e32 v29, s17, v28
	s_mov_b64 s[10:11], -1
	s_andn2_b64 vcc, exec, s[8:9]
	v_ashrrev_i32_e32 v76, 31, v70
	v_mul_lo_u32 v75, s1, v70
	v_ashrrev_i32_e32 v74, 31, v67
	v_mul_lo_u32 v73, s1, v67
	v_ashrrev_i32_e32 v72, 31, v66
	v_mul_lo_u32 v71, s1, v66
	v_ashrrev_i32_e32 v69, 31, v65
	v_mul_lo_u32 v68, s1, v65
	v_ashrrev_i32_e32 v64, 31, v60
	v_mul_lo_u32 v63, s1, v60
	v_ashrrev_i32_e32 v62, 31, v59
	v_mul_lo_u32 v61, s1, v59
	v_ashrrev_i32_e32 v58, 31, v54
	v_mul_lo_u32 v57, s1, v54
	v_ashrrev_i32_e32 v56, 31, v53
	v_mul_lo_u32 v55, s1, v53
	v_ashrrev_i32_e32 v52, 31, v48
	v_mul_lo_u32 v51, s1, v48
	v_ashrrev_i32_e32 v50, 31, v47
	v_mul_lo_u32 v49, s1, v47
	v_ashrrev_i32_e32 v46, 31, v42
	v_mul_lo_u32 v45, s1, v42
	v_ashrrev_i32_e32 v44, 31, v41
	v_mul_lo_u32 v43, s1, v41
	v_ashrrev_i32_e32 v40, 31, v36
	v_mul_lo_u32 v39, s1, v36
	v_ashrrev_i32_e32 v38, 31, v35
	v_mul_lo_u32 v37, s1, v35
	v_ashrrev_i32_e32 v34, 31, v30
	v_mul_lo_u32 v33, s1, v30
	v_ashrrev_i32_e32 v32, 31, v29
	v_mul_lo_u32 v31, s1, v29
	s_cbranch_vccz .LBB0_250
	ds_read_b64 v[8:9], v229 offset:63760
	s_ashr_i32 s3, s2, 31
	s_add_i32 s1, s17, 0xfffffa00
	s_lshl_b64 s[8:9], s[2:3], 1
	v_add_u32_e32 v78, s1, v1
	s_waitcnt lgkmcnt(0)
	v_lshl_add_u64 v[8:9], v[8:9], 0, s[8:9]
	v_lshl_add_u64 v[8:9], v[8:9], 0, v[228:229]
	s_mov_b64 s[10:11], 0xf1d4000
	v_ashrrev_i32_e32 v79, 31, v78
	v_lshl_add_u64 v[10:11], v[8:9], 0, s[10:11]
	v_lshlrev_b64 v[78:79], 11, v[78:79]
	v_lshl_add_u64 v[78:79], v[10:11], 0, v[78:79]
	global_load_ushort v110, v[78:79], off
	v_lshl_add_u64 v[8:9], v[4:5], 0, s[8:9]
	v_mul_lo_u32 v80, s0, v76
	v_mad_u64_u32 v[126:127], s[8:9], s0, v70, 0
	v_lshl_add_u64 v[8:9], v[8:9], 0, v[228:229]
	v_add3_u32 v127, v127, v80, v75
	v_lshl_add_u64 v[126:127], v[126:127], 1, v[8:9]
	v_mul_lo_u32 v80, s0, v74
	s_mov_b64 s[10:11], 0
	v_add_u32_e32 v78, s1, v14
	v_ashrrev_i32_e32 v79, 31, v78
	v_lshlrev_b64 v[78:79], 11, v[78:79]
	v_lshl_add_u64 v[78:79], v[10:11], 0, v[78:79]
	global_load_ushort v111, v[78:79], off
	v_mad_u64_u32 v[128:129], s[8:9], s0, v67, 0
	v_add3_u32 v129, v129, v80, v73
	v_lshl_add_u64 v[128:129], v[128:129], 1, v[8:9]
	v_mul_lo_u32 v80, s0, v72
	v_add_u32_e32 v78, s1, v15
	v_ashrrev_i32_e32 v79, 31, v78
	v_lshlrev_b64 v[78:79], 11, v[78:79]
	v_lshl_add_u64 v[78:79], v[10:11], 0, v[78:79]
	global_load_ushort v112, v[78:79], off
	v_mad_u64_u32 v[130:131], s[8:9], s0, v66, 0
	v_add3_u32 v131, v131, v80, v71
	v_lshl_add_u64 v[130:131], v[130:131], 1, v[8:9]
	v_mul_lo_u32 v80, s0, v69
	v_add_u32_e32 v78, s1, v16
	v_ashrrev_i32_e32 v79, 31, v78
	v_lshlrev_b64 v[78:79], 11, v[78:79]
	v_lshl_add_u64 v[78:79], v[10:11], 0, v[78:79]
	global_load_ushort v113, v[78:79], off
	v_mad_u64_u32 v[132:133], s[8:9], s0, v65, 0
	v_add3_u32 v133, v133, v80, v68
	v_lshl_add_u64 v[132:133], v[132:133], 1, v[8:9]
	v_mul_lo_u32 v80, s0, v64
	v_add_u32_e32 v78, s1, v17
	v_ashrrev_i32_e32 v79, 31, v78
	v_lshlrev_b64 v[78:79], 11, v[78:79]
	v_lshl_add_u64 v[78:79], v[10:11], 0, v[78:79]
	global_load_ushort v114, v[78:79], off
	v_mad_u64_u32 v[134:135], s[8:9], s0, v60, 0
	v_add3_u32 v135, v135, v80, v63
	v_lshl_add_u64 v[134:135], v[134:135], 1, v[8:9]
	v_mul_lo_u32 v80, s0, v62
	v_add_u32_e32 v78, s1, v18
	v_ashrrev_i32_e32 v79, 31, v78
	v_lshlrev_b64 v[78:79], 11, v[78:79]
	v_lshl_add_u64 v[78:79], v[10:11], 0, v[78:79]
	global_load_ushort v115, v[78:79], off
	v_mad_u64_u32 v[136:137], s[8:9], s0, v59, 0
	v_add3_u32 v137, v137, v80, v61
	v_lshl_add_u64 v[136:137], v[136:137], 1, v[8:9]
	v_mul_lo_u32 v80, s0, v58
	v_add_u32_e32 v78, s1, v19
	v_ashrrev_i32_e32 v79, 31, v78
	v_lshlrev_b64 v[78:79], 11, v[78:79]
	v_lshl_add_u64 v[78:79], v[10:11], 0, v[78:79]
	global_load_ushort v116, v[78:79], off
	v_mad_u64_u32 v[138:139], s[8:9], s0, v54, 0
	v_add3_u32 v139, v139, v80, v57
	v_lshl_add_u64 v[138:139], v[138:139], 1, v[8:9]
	v_mul_lo_u32 v80, s0, v56
	v_add_u32_e32 v78, s1, v20
	v_ashrrev_i32_e32 v79, 31, v78
	v_lshlrev_b64 v[78:79], 11, v[78:79]
	v_lshl_add_u64 v[78:79], v[10:11], 0, v[78:79]
	global_load_ushort v117, v[78:79], off
	v_mad_u64_u32 v[140:141], s[8:9], s0, v53, 0
	v_add3_u32 v141, v141, v80, v55
	v_lshl_add_u64 v[140:141], v[140:141], 1, v[8:9]
	v_mul_lo_u32 v80, s0, v52
	v_add_u32_e32 v78, s1, v21
	v_ashrrev_i32_e32 v79, 31, v78
	v_lshlrev_b64 v[78:79], 11, v[78:79]
	v_lshl_add_u64 v[78:79], v[10:11], 0, v[78:79]
	global_load_ushort v118, v[78:79], off
	v_mad_u64_u32 v[142:143], s[8:9], s0, v48, 0
	v_add3_u32 v143, v143, v80, v51
	v_lshl_add_u64 v[142:143], v[142:143], 1, v[8:9]
	v_mul_lo_u32 v80, s0, v50
	v_add_u32_e32 v78, s1, v22
	v_ashrrev_i32_e32 v79, 31, v78
	v_lshlrev_b64 v[78:79], 11, v[78:79]
	v_lshl_add_u64 v[78:79], v[10:11], 0, v[78:79]
	global_load_ushort v119, v[78:79], off
	v_mad_u64_u32 v[144:145], s[8:9], s0, v47, 0
	v_add3_u32 v145, v145, v80, v49
	v_lshl_add_u64 v[144:145], v[144:145], 1, v[8:9]
	v_mul_lo_u32 v80, s0, v46
	v_add_u32_e32 v78, s1, v23
	v_ashrrev_i32_e32 v79, 31, v78
	v_lshlrev_b64 v[78:79], 11, v[78:79]
	v_lshl_add_u64 v[78:79], v[10:11], 0, v[78:79]
	global_load_ushort v120, v[78:79], off
	v_mad_u64_u32 v[146:147], s[8:9], s0, v42, 0
	v_add3_u32 v147, v147, v80, v45
	v_lshl_add_u64 v[146:147], v[146:147], 1, v[8:9]
	v_mul_lo_u32 v80, s0, v44
	v_add_u32_e32 v78, s1, v24
	v_ashrrev_i32_e32 v79, 31, v78
	v_lshlrev_b64 v[78:79], 11, v[78:79]
	v_lshl_add_u64 v[78:79], v[10:11], 0, v[78:79]
	global_load_ushort v121, v[78:79], off
	v_mad_u64_u32 v[148:149], s[8:9], s0, v41, 0
	v_add3_u32 v149, v149, v80, v43
	v_lshl_add_u64 v[148:149], v[148:149], 1, v[8:9]
	v_mul_lo_u32 v80, s0, v40
	v_add_u32_e32 v78, s1, v25
	v_ashrrev_i32_e32 v79, 31, v78
	v_lshlrev_b64 v[78:79], 11, v[78:79]
	v_lshl_add_u64 v[78:79], v[10:11], 0, v[78:79]
	global_load_ushort v122, v[78:79], off
	v_mad_u64_u32 v[150:151], s[8:9], s0, v36, 0
	v_add3_u32 v151, v151, v80, v39
	v_lshl_add_u64 v[150:151], v[150:151], 1, v[8:9]
	v_mul_lo_u32 v80, s0, v38
	v_add_u32_e32 v78, s1, v26
	v_ashrrev_i32_e32 v79, 31, v78
	v_lshlrev_b64 v[78:79], 11, v[78:79]
	v_lshl_add_u64 v[78:79], v[10:11], 0, v[78:79]
	global_load_ushort v123, v[78:79], off
	v_mad_u64_u32 v[152:153], s[8:9], s0, v35, 0
	v_add3_u32 v153, v153, v80, v37
	v_lshl_add_u64 v[152:153], v[152:153], 1, v[8:9]
	v_mul_lo_u32 v80, s0, v34
	v_add_u32_e32 v78, s1, v27
	v_ashrrev_i32_e32 v79, 31, v78
	v_lshlrev_b64 v[78:79], 11, v[78:79]
	v_lshl_add_u64 v[78:79], v[10:11], 0, v[78:79]
	global_load_ushort v124, v[78:79], off
	v_mad_u64_u32 v[154:155], s[8:9], s0, v30, 0
	v_add3_u32 v155, v155, v80, v33
	v_lshl_add_u64 v[154:155], v[154:155], 1, v[8:9]
	v_add_u32_e32 v78, s1, v28
	v_ashrrev_i32_e32 v79, 31, v78
	v_lshlrev_b64 v[78:79], 11, v[78:79]
	v_lshl_add_u64 v[10:11], v[10:11], 0, v[78:79]
	global_load_ushort v125, v[10:11], off
	v_mul_lo_u32 v78, s0, v32
	v_mad_u64_u32 v[10:11], s[8:9], s0, v29, 0
	v_add3_u32 v11, v11, v78, v31
	v_lshl_add_u64 v[156:157], v[10:11], 1, v[8:9]
	s_waitcnt vmcnt(0)
	global_store_short v[126:127], v110, off
	global_store_short v[128:129], v111, off
	global_store_short v[130:131], v112, off
	global_store_short v[132:133], v113, off
	global_store_short v[134:135], v114, off
	global_store_short v[136:137], v115, off
	global_store_short v[138:139], v116, off
	global_store_short v[140:141], v117, off
	global_store_short v[142:143], v118, off
	global_store_short v[144:145], v119, off
	global_store_short v[146:147], v120, off
	global_store_short v[148:149], v121, off
	global_store_short v[150:151], v122, off
	global_store_short v[152:153], v123, off
	global_store_short v[154:155], v124, off
	global_store_short v[156:157], v125, off
	s_barrier
.LBB0_250:
	s_andn2_b64 vcc, exec, s[10:11]
	s_cbranch_vccnz .LBB0_226
	s_ashr_i32 s1, s17, 1
	s_andn2_b32 s1, s1, 63
	v_add_u32_e32 v9, s1, v12
	s_lshr_b32 s1, s17, 1
	s_and_b32 s1, s1, 32
	v_add_u32_e32 v8, s16, v0
	v_or3_b32 v9, v9, s1, v13
	v_cndmask_b32_e64 v8, v8, v9, s[6:7]
	v_add_u32_e32 v9, s2, v1
	v_ashrrev_i32_e32 v10, 31, v9
	v_mul_lo_u32 v77, s4, v10
	v_mul_lo_u32 v78, s5, v9
	v_mad_u64_u32 v[10:11], s[6:7], s4, v9, 0
	v_add3_u32 v11, v11, v77, v78
	v_ashrrev_i32_e32 v9, 31, v8
	v_lshl_add_u64 v[10:11], v[10:11], 2, v[6:7]
	v_lshlrev_b64 v[8:9], 2, v[8:9]
	v_lshl_add_u64 v[10:11], v[10:11], 0, v[8:9]
	global_load_dword v110, v[10:11], off
	s_ashr_i32 s3, s2, 31
	v_mul_lo_u32 v76, s0, v76
	v_add_u32_e32 v10, s2, v14
	v_ashrrev_i32_e32 v11, 31, v10
	v_mul_lo_u32 v77, s4, v11
	v_mul_lo_u32 v78, s5, v10
	v_mad_u64_u32 v[10:11], s[6:7], s4, v10, 0
	v_add3_u32 v11, v11, v77, v78
	v_lshl_add_u64 v[10:11], v[10:11], 2, v[6:7]
	v_lshl_add_u64 v[10:11], v[10:11], 0, v[8:9]
	global_load_dword v111, v[10:11], off
	v_add_u32_e32 v10, s2, v15
	v_ashrrev_i32_e32 v11, 31, v10
	v_mul_lo_u32 v77, s4, v11
	v_mul_lo_u32 v78, s5, v10
	v_mad_u64_u32 v[10:11], s[6:7], s4, v10, 0
	v_add3_u32 v11, v11, v77, v78
	v_lshl_add_u64 v[10:11], v[10:11], 2, v[6:7]
	v_lshl_add_u64 v[10:11], v[10:11], 0, v[8:9]
	global_load_dword v112, v[10:11], off
	v_add_u32_e32 v10, s2, v16
	v_ashrrev_i32_e32 v11, 31, v10
	v_mul_lo_u32 v77, s4, v11
	v_mul_lo_u32 v78, s5, v10
	v_mad_u64_u32 v[10:11], s[6:7], s4, v10, 0
	v_add3_u32 v11, v11, v77, v78
	v_lshl_add_u64 v[10:11], v[10:11], 2, v[6:7]
	v_lshl_add_u64 v[10:11], v[10:11], 0, v[8:9]
	global_load_dword v113, v[10:11], off
	v_add_u32_e32 v10, s2, v17
	v_ashrrev_i32_e32 v11, 31, v10
	v_mul_lo_u32 v77, s4, v11
	v_mul_lo_u32 v78, s5, v10
	v_mad_u64_u32 v[10:11], s[6:7], s4, v10, 0
	v_add3_u32 v11, v11, v77, v78
	v_lshl_add_u64 v[10:11], v[10:11], 2, v[6:7]
	v_lshl_add_u64 v[10:11], v[10:11], 0, v[8:9]
	global_load_dword v114, v[10:11], off
	v_add_u32_e32 v10, s2, v18
	v_ashrrev_i32_e32 v11, 31, v10
	v_mul_lo_u32 v77, s4, v11
	v_mul_lo_u32 v78, s5, v10
	v_mad_u64_u32 v[10:11], s[6:7], s4, v10, 0
	v_add3_u32 v11, v11, v77, v78
	v_lshl_add_u64 v[10:11], v[10:11], 2, v[6:7]
	v_lshl_add_u64 v[10:11], v[10:11], 0, v[8:9]
	global_load_dword v115, v[10:11], off
	v_add_u32_e32 v10, s2, v19
	v_ashrrev_i32_e32 v11, 31, v10
	v_mul_lo_u32 v77, s4, v11
	v_mul_lo_u32 v78, s5, v10
	v_mad_u64_u32 v[10:11], s[6:7], s4, v10, 0
	v_add3_u32 v11, v11, v77, v78
	v_lshl_add_u64 v[10:11], v[10:11], 2, v[6:7]
	v_lshl_add_u64 v[10:11], v[10:11], 0, v[8:9]
	global_load_dword v116, v[10:11], off
	v_add_u32_e32 v10, s2, v20
	v_ashrrev_i32_e32 v11, 31, v10
	v_mul_lo_u32 v77, s4, v11
	v_mul_lo_u32 v78, s5, v10
	v_mad_u64_u32 v[10:11], s[6:7], s4, v10, 0
	v_add3_u32 v11, v11, v77, v78
	v_lshl_add_u64 v[10:11], v[10:11], 2, v[6:7]
	v_lshl_add_u64 v[10:11], v[10:11], 0, v[8:9]
	global_load_dword v117, v[10:11], off
	v_add_u32_e32 v10, s2, v21
	v_ashrrev_i32_e32 v11, 31, v10
	v_mul_lo_u32 v77, s4, v11
	v_mul_lo_u32 v78, s5, v10
	v_mad_u64_u32 v[10:11], s[6:7], s4, v10, 0
	v_add3_u32 v11, v11, v77, v78
	v_lshl_add_u64 v[10:11], v[10:11], 2, v[6:7]
	v_lshl_add_u64 v[10:11], v[10:11], 0, v[8:9]
	global_load_dword v118, v[10:11], off
	v_add_u32_e32 v10, s2, v22
	v_ashrrev_i32_e32 v11, 31, v10
	v_mul_lo_u32 v77, s4, v11
	v_mul_lo_u32 v78, s5, v10
	v_mad_u64_u32 v[10:11], s[6:7], s4, v10, 0
	v_add3_u32 v11, v11, v77, v78
	v_lshl_add_u64 v[10:11], v[10:11], 2, v[6:7]
	v_lshl_add_u64 v[10:11], v[10:11], 0, v[8:9]
	global_load_dword v119, v[10:11], off
	v_add_u32_e32 v10, s2, v23
	v_ashrrev_i32_e32 v11, 31, v10
	v_mul_lo_u32 v77, s4, v11
	v_mul_lo_u32 v78, s5, v10
	v_mad_u64_u32 v[10:11], s[6:7], s4, v10, 0
	v_add3_u32 v11, v11, v77, v78
	v_lshl_add_u64 v[10:11], v[10:11], 2, v[6:7]
	v_lshl_add_u64 v[10:11], v[10:11], 0, v[8:9]
	global_load_dword v120, v[10:11], off
	v_add_u32_e32 v10, s2, v24
	v_ashrrev_i32_e32 v11, 31, v10
	v_mul_lo_u32 v77, s4, v11
	v_mul_lo_u32 v78, s5, v10
	v_mad_u64_u32 v[10:11], s[6:7], s4, v10, 0
	v_add3_u32 v11, v11, v77, v78
	v_lshl_add_u64 v[10:11], v[10:11], 2, v[6:7]
	v_lshl_add_u64 v[10:11], v[10:11], 0, v[8:9]
	global_load_dword v121, v[10:11], off
	v_add_u32_e32 v10, s2, v25
	v_ashrrev_i32_e32 v11, 31, v10
	v_mul_lo_u32 v77, s4, v11
	v_mul_lo_u32 v78, s5, v10
	v_mad_u64_u32 v[10:11], s[6:7], s4, v10, 0
	v_add3_u32 v11, v11, v77, v78
	v_lshl_add_u64 v[10:11], v[10:11], 2, v[6:7]
	v_lshl_add_u64 v[10:11], v[10:11], 0, v[8:9]
	global_load_dword v122, v[10:11], off
	v_add_u32_e32 v10, s2, v26
	v_ashrrev_i32_e32 v11, 31, v10
	v_mul_lo_u32 v77, s4, v11
	v_mul_lo_u32 v78, s5, v10
	v_mad_u64_u32 v[10:11], s[6:7], s4, v10, 0
	v_add3_u32 v11, v11, v77, v78
	v_lshl_add_u64 v[10:11], v[10:11], 2, v[6:7]
	v_lshl_add_u64 v[10:11], v[10:11], 0, v[8:9]
	global_load_dword v123, v[10:11], off
	v_add_u32_e32 v10, s2, v27
	v_ashrrev_i32_e32 v11, 31, v10
	v_mul_lo_u32 v77, s4, v11
	v_mul_lo_u32 v78, s5, v10
	v_mad_u64_u32 v[10:11], s[6:7], s4, v10, 0
	v_add3_u32 v11, v11, v77, v78
	v_lshl_add_u64 v[10:11], v[10:11], 2, v[6:7]
	v_lshl_add_u64 v[10:11], v[10:11], 0, v[8:9]
	global_load_dword v124, v[10:11], off
	v_add_u32_e32 v10, s2, v28
	v_ashrrev_i32_e32 v11, 31, v10
	v_mul_lo_u32 v77, s4, v11
	v_mul_lo_u32 v78, s5, v10
	v_mad_u64_u32 v[10:11], s[4:5], s4, v10, 0
	v_add3_u32 v11, v11, v77, v78
	v_lshl_add_u64 v[6:7], v[10:11], 2, v[6:7]
	v_lshl_add_u64 v[6:7], v[6:7], 0, v[8:9]
	global_load_dword v125, v[6:7], off
	s_lshl_b64 s[2:3], s[2:3], 1
	v_lshl_add_u64 v[4:5], v[4:5], 0, s[2:3]
	v_lshl_add_u64 v[4:5], v[4:5], 0, v[228:229]
	s_waitcnt vmcnt(0)
	ds_write_b32 v2, v110
	ds_write_b32 v2, v111 offset:1040
	ds_write_b32 v2, v112 offset:2080
	ds_write_b32 v2, v113 offset:3120
	ds_write_b32 v2, v114 offset:4160
	ds_write_b32 v2, v115 offset:5200
	ds_write_b32 v2, v116 offset:6240
	ds_write_b32 v2, v117 offset:7280
	ds_write_b32 v2, v118 offset:8320
	ds_write_b32 v2, v119 offset:9360
	ds_write_b32 v2, v120 offset:10400
	ds_write_b32 v2, v121 offset:11440
	ds_write_b32 v2, v122 offset:12480
	ds_write_b32 v2, v123 offset:13520
	ds_write_b32 v2, v124 offset:14560
	ds_write_b32 v2, v125 offset:15600
	s_waitcnt lgkmcnt(0)
	s_barrier
	ds_read2_b32 v[6:7], v3 offset1:4
	ds_read2_b32 v[8:9], v3 offset0:8 offset1:12
	s_waitcnt lgkmcnt(1)
	v_bfe_u32 v10, v6, 16, 1
	v_add3_u32 v6, v6, v10, s89
	v_mad_u64_u32 v[10:11], s[2:3], s0, v70, 0
	v_add3_u32 v11, v11, v76, v75
	v_lshl_add_u64 v[10:11], v[10:11], 1, v[4:5]
	global_store_short_d16_hi v[10:11], v6, off
	v_bfe_u32 v6, v7, 16, 1
	v_add3_u32 v10, v7, v6, s89
	v_mul_lo_u32 v11, s0, v74
	v_mad_u64_u32 v[6:7], s[2:3], s0, v67, 0
	v_add3_u32 v7, v7, v11, v73
	v_lshl_add_u64 v[6:7], v[6:7], 1, v[4:5]
	global_store_short_d16_hi v[6:7], v10, off
	s_waitcnt lgkmcnt(0)
	v_bfe_u32 v6, v8, 16, 1
	v_add3_u32 v8, v8, v6, s89
	v_mul_lo_u32 v10, s0, v72
	v_mad_u64_u32 v[6:7], s[2:3], s0, v66, 0
	v_add3_u32 v7, v7, v10, v71
	v_lshl_add_u64 v[6:7], v[6:7], 1, v[4:5]
	global_store_short_d16_hi v[6:7], v8, off
	v_bfe_u32 v6, v9, 16, 1
	v_add3_u32 v8, v9, v6, s89
	v_mul_lo_u32 v9, s0, v69
	v_mad_u64_u32 v[6:7], s[2:3], s0, v65, 0
	v_add3_u32 v7, v7, v9, v68
	v_lshl_add_u64 v[6:7], v[6:7], 1, v[4:5]
	global_store_short_d16_hi v[6:7], v8, off
	ds_read2_b32 v[6:7], v3 offset0:16 offset1:20
	v_mul_lo_u32 v10, s0, v64
	s_waitcnt lgkmcnt(0)
	v_bfe_u32 v8, v6, 16, 1
	v_add3_u32 v6, v6, v8, s89
	v_mad_u64_u32 v[8:9], s[2:3], s0, v60, 0
	v_add3_u32 v9, v9, v10, v63
	v_lshl_add_u64 v[8:9], v[8:9], 1, v[4:5]
	global_store_short_d16_hi v[8:9], v6, off
	v_bfe_u32 v6, v7, 16, 1
	v_add3_u32 v8, v7, v6, s89
	v_mul_lo_u32 v9, s0, v62
	v_mad_u64_u32 v[6:7], s[2:3], s0, v59, 0
	v_add3_u32 v7, v7, v9, v61
	v_lshl_add_u64 v[6:7], v[6:7], 1, v[4:5]
	global_store_short_d16_hi v[6:7], v8, off
	ds_read2_b32 v[6:7], v3 offset0:24 offset1:28
	v_mul_lo_u32 v10, s0, v58
	s_waitcnt lgkmcnt(0)
	v_bfe_u32 v8, v6, 16, 1
	v_add3_u32 v6, v6, v8, s89
	v_mad_u64_u32 v[8:9], s[2:3], s0, v54, 0
	v_add3_u32 v9, v9, v10, v57
	v_lshl_add_u64 v[8:9], v[8:9], 1, v[4:5]
	global_store_short_d16_hi v[8:9], v6, off
	v_bfe_u32 v6, v7, 16, 1
	v_add3_u32 v8, v7, v6, s89
	v_mul_lo_u32 v9, s0, v56
	v_mad_u64_u32 v[6:7], s[2:3], s0, v53, 0
	v_add3_u32 v7, v7, v9, v55
	v_lshl_add_u64 v[6:7], v[6:7], 1, v[4:5]
	global_store_short_d16_hi v[6:7], v8, off
	ds_read2_b32 v[6:7], v3 offset0:32 offset1:36
	v_mul_lo_u32 v10, s0, v52
	s_waitcnt lgkmcnt(0)
	v_bfe_u32 v8, v6, 16, 1
	v_add3_u32 v6, v6, v8, s89
	v_mad_u64_u32 v[8:9], s[2:3], s0, v48, 0
	v_add3_u32 v9, v9, v10, v51
	v_lshl_add_u64 v[8:9], v[8:9], 1, v[4:5]
	global_store_short_d16_hi v[8:9], v6, off
	v_bfe_u32 v6, v7, 16, 1
	v_add3_u32 v8, v7, v6, s89
	v_mul_lo_u32 v9, s0, v50
	v_mad_u64_u32 v[6:7], s[2:3], s0, v47, 0
	v_add3_u32 v7, v7, v9, v49
	v_lshl_add_u64 v[6:7], v[6:7], 1, v[4:5]
	global_store_short_d16_hi v[6:7], v8, off
	ds_read2_b32 v[6:7], v3 offset0:40 offset1:44
	v_mul_lo_u32 v10, s0, v46
	s_waitcnt lgkmcnt(0)
	v_bfe_u32 v8, v6, 16, 1
	v_add3_u32 v6, v6, v8, s89
	v_mad_u64_u32 v[8:9], s[2:3], s0, v42, 0
	v_add3_u32 v9, v9, v10, v45
	v_lshl_add_u64 v[8:9], v[8:9], 1, v[4:5]
	global_store_short_d16_hi v[8:9], v6, off
	v_bfe_u32 v6, v7, 16, 1
	v_add3_u32 v8, v7, v6, s89
	v_mul_lo_u32 v9, s0, v44
	v_mad_u64_u32 v[6:7], s[2:3], s0, v41, 0
	v_add3_u32 v7, v7, v9, v43
	v_lshl_add_u64 v[6:7], v[6:7], 1, v[4:5]
	global_store_short_d16_hi v[6:7], v8, off
	ds_read2_b32 v[6:7], v3 offset0:48 offset1:52
	v_mul_lo_u32 v10, s0, v40
	s_waitcnt lgkmcnt(0)
	v_bfe_u32 v8, v6, 16, 1
	v_add3_u32 v6, v6, v8, s89
	v_mad_u64_u32 v[8:9], s[2:3], s0, v36, 0
	v_add3_u32 v9, v9, v10, v39
	v_lshl_add_u64 v[8:9], v[8:9], 1, v[4:5]
	global_store_short_d16_hi v[8:9], v6, off
	v_bfe_u32 v6, v7, 16, 1
	v_add3_u32 v8, v7, v6, s89
	v_mul_lo_u32 v9, s0, v38
	v_mad_u64_u32 v[6:7], s[2:3], s0, v35, 0
	v_add3_u32 v7, v7, v9, v37
	v_lshl_add_u64 v[6:7], v[6:7], 1, v[4:5]
	global_store_short_d16_hi v[6:7], v8, off
	ds_read2_b32 v[6:7], v3 offset0:56 offset1:60
	v_mul_lo_u32 v10, s0, v34
	s_waitcnt lgkmcnt(0)
	v_bfe_u32 v8, v6, 16, 1
	v_add3_u32 v6, v6, v8, s89
	v_mad_u64_u32 v[8:9], s[2:3], s0, v30, 0
	v_add3_u32 v9, v9, v10, v33
	v_lshl_add_u64 v[8:9], v[8:9], 1, v[4:5]
	global_store_short_d16_hi v[8:9], v6, off
	v_bfe_u32 v6, v7, 16, 1
	v_add3_u32 v8, v7, v6, s89
	v_mul_lo_u32 v9, s0, v32
	v_mad_u64_u32 v[6:7], s[0:1], s0, v29, 0
	v_add3_u32 v7, v7, v9, v31
	v_lshl_add_u64 v[4:5], v[6:7], 1, v[4:5]
	global_store_short_d16_hi v[4:5], v8, off
	s_barrier
	s_branch .LBB0_226
.LBB0_252:
	v_readlane_b32 s0, v255, 10
	v_readlane_b32 s1, v255, 11
	s_xor_b64 s[0:1], s[0:1], -1
	v_writelane_b32 v255, s0, 25
	s_mov_b32 s3, s51
	v_mov_b32_e32 v8, v231
	v_writelane_b32 v255, s1, 26
	ds_read_b64 v[0:1], v229 offset:63560
	v_readlane_b32 s0, v255, 9
	s_lshl_b32 s2, s0, 10
	v_writelane_b32 v255, s2, 27
	ds_read_b64 v[6:7], v229 offset:63760
	s_waitcnt lgkmcnt(0)
	ds_read_b64 v[4:5], v229 offset:63760
	ds_read_b64 v[2:3], v229 offset:63760
	v_writelane_b32 v255, s3, 28
	s_mulk_i32 s0, 0x4800
	s_mov_b32 s1, s51
	v_writelane_b32 v255, s0, 29
	v_ashrrev_i32_e32 v9, 6, v8
	s_nop 0
	v_writelane_b32 v255, s1, 30
	s_mov_b32 s0, s76
	s_nop 0
	v_lshl_add_u32 v20, s0, 2, v9
	v_cmp_gt_i32_e32 vcc, s94, v20
	s_and_saveexec_b64 s[2:3], vcc
	s_cbranch_execz .LBB0_263
	v_and_b32_e32 v9, 64, v244
	v_add_u32_e32 v9, 64, v9
	v_xor_b32_e32 v10, 32, v244
	v_cmp_lt_i32_e32 vcc, v10, v9
	v_readlane_b32 s0, v255, 29
	v_readlane_b32 s1, v255, 30
	v_cndmask_b32_e32 v10, v244, v10, vcc
	v_lshlrev_b32_e32 v37, 2, v10
	v_xor_b32_e32 v10, 16, v244
	v_cmp_lt_i32_e32 vcc, v10, v9
	s_lshl_b64 s[0:1], s[0:1], 2
	s_waitcnt lgkmcnt(0)
	v_lshl_add_u64 v[2:3], v[2:3], 0, s[0:1]
	v_cndmask_b32_e32 v10, v244, v10, vcc
	v_lshlrev_b32_e32 v44, 2, v10
	v_xor_b32_e32 v10, 8, v244
	v_cmp_lt_i32_e32 vcc, v10, v9
	s_mov_b64 s[0:1], 0x2a20000
	v_lshl_add_u64 v[24:25], v[2:3], 0, s[0:1]
	v_cndmask_b32_e32 v10, v244, v10, vcc
	v_lshlrev_b32_e32 v45, 2, v10
	v_xor_b32_e32 v10, 4, v244
	v_cmp_lt_i32_e32 vcc, v10, v9
	v_readlane_b32 s0, v255, 27
	v_readlane_b32 s1, v255, 28
	v_cndmask_b32_e32 v10, v244, v10, vcc
	v_lshlrev_b32_e32 v46, 2, v10
	v_xor_b32_e32 v10, 2, v244
	s_lshl_b64 s[0:1], s[0:1], 2
	v_lshlrev_b32_e32 v8, 2, v8
	v_cmp_lt_i32_e32 vcc, v10, v9
	v_lshl_add_u64 v[22:23], v[6:7], 0, s[56:57]
	v_lshl_add_u64 v[6:7], v[0:1], 0, s[0:1]
	ds_read_b128 v[0:3], v229 offset:63488
	v_and_b32_e32 v8, 0xfc, v8
	v_cndmask_b32_e32 v10, v244, v10, vcc
	v_lshlrev_b32_e32 v47, 2, v10
	v_xor_b32_e32 v10, 1, v244
	v_lshlrev_b32_e32 v228, 2, v8
	v_cmp_lt_i32_e32 vcc, v10, v9
	v_lshl_add_u64 v[26:27], v[6:7], 0, v[228:229]
	v_lshlrev_b32_e32 v228, 1, v8
	v_cndmask_b32_e32 v9, v244, v10, vcc
	v_or_b32_e32 v6, 0x100, v8
	v_or_b32_e32 v10, 0x200, v8
	v_or_b32_e32 v12, 0x300, v8
	v_lshl_add_u64 v[4:5], v[4:5], 0, v[228:229]
	v_lshlrev_b32_e32 v48, 2, v9
	v_lshl_add_u64 v[28:29], v[4:5], 0, s[58:59]
	s_mov_b64 s[4:5], 0
	v_lshlrev_b32_e32 v228, 2, v8
	v_lshlrev_b32_e32 v30, 2, v6
	v_lshlrev_b32_e32 v32, 2, v10
	v_lshlrev_b32_e32 v34, 2, v12
	s_cmp_eq_u32 s77, 0x800
	s_cbranch_scc0 .LBB0_256
	v_readfirstlane_b32 s0, v20
	v_readfirstlane_b32 s10, v24
	v_readfirstlane_b32 s11, v25
	s_waitcnt lgkmcnt(0)
	v_readlane_b32 s6, v255, 25
	v_readlane_b32 s7, v255, 26
	s_mov_b32 s88, 0x7060302
	v_readfirstlane_b32 s28, v22
	v_readfirstlane_b32 s29, v23
	v_readfirstlane_b32 s24, v0
	v_readfirstlane_b32 s25, v1
	v_readfirstlane_b32 s26, v2
	v_readfirstlane_b32 s27, v3
	s_add_u32 s1, s0, 0x0
	s_cmp_lt_u32 s1, 4096
	s_cselect_b64 s[14:15], s[24:25], s[26:27]
	s_cselect_b32 s9, 0, 0x1000000
	s_cmp_lg_u64 s[6:7], 0
	s_cselect_b64 s[14:15], s[28:29], s[14:15]
	s_cselect_b32 s9, 0, s9
	s_lshl_b32 s1, s1, 12
	s_sub_u32 s1, s1, s9
	s_add_u32 s14, s14, s1
	s_addc_u32 s15, s15, 0
	global_load_dwordx4 v[64:67], v228, s[14:15]
	global_load_dwordx4 v[68:71], v228, s[14:15] offset:1024
	global_load_dwordx4 v[72:75], v228, s[14:15] offset:2048
	global_load_dwordx4 v[76:79], v228, s[14:15] offset:3072
	s_add_u32 s1, s0, 0x800
	s_cmp_lt_u32 s1, 4096
	s_cselect_b64 s[14:15], s[24:25], s[26:27]
	s_cselect_b32 s9, 0, 0x1000000
	s_cmp_lg_u64 s[6:7], 0
	s_cselect_b64 s[14:15], s[28:29], s[14:15]
	s_cselect_b32 s9, 0, s9
	s_lshl_b32 s1, s1, 12
	s_sub_u32 s1, s1, s9
	s_add_u32 s14, s14, s1
	s_addc_u32 s15, s15, 0
	global_load_dwordx4 v[80:83], v228, s[14:15]
	global_load_dwordx4 v[84:87], v228, s[14:15] offset:1024
	global_load_dwordx4 v[88:91], v228, s[14:15] offset:2048
	global_load_dwordx4 v[92:95], v228, s[14:15] offset:3072
	s_add_u32 s1, s0, 0x1000
	s_cmp_lt_u32 s1, 4096
	s_cselect_b64 s[14:15], s[24:25], s[26:27]
	s_cselect_b32 s9, 0, 0x1000000
	s_cmp_lg_u64 s[6:7], 0
	s_cselect_b64 s[14:15], s[28:29], s[14:15]
	s_cselect_b32 s9, 0, s9
	s_lshl_b32 s1, s1, 12
	s_sub_u32 s1, s1, s9
	s_add_u32 s14, s14, s1
	s_addc_u32 s15, s15, 0
	global_load_dwordx4 v[96:99], v228, s[14:15]
	global_load_dwordx4 v[100:103], v228, s[14:15] offset:1024
	global_load_dwordx4 v[104:107], v228, s[14:15] offset:2048
	global_load_dwordx4 v[108:111], v228, s[14:15] offset:3072
	s_add_u32 s1, s0, 0x1800
	s_cmp_lt_u32 s1, 4096
	s_cselect_b64 s[14:15], s[24:25], s[26:27]
	s_cselect_b32 s9, 0, 0x1000000
	s_cmp_lg_u64 s[6:7], 0
	s_cselect_b64 s[14:15], s[28:29], s[14:15]
	s_cselect_b32 s9, 0, s9
	s_lshl_b32 s1, s1, 12
	s_sub_u32 s1, s1, s9
	s_add_u32 s14, s14, s1
	s_addc_u32 s15, s15, 0
	global_load_dwordx4 v[112:115], v228, s[14:15]
	global_load_dwordx4 v[116:119], v228, s[14:15] offset:1024
	global_load_dwordx4 v[120:123], v228, s[14:15] offset:2048
	global_load_dwordx4 v[124:127], v228, s[14:15] offset:3072
	global_load_dwordx4 v[128:131], v[26:27], off
	global_load_dwordx4 v[132:135], v[26:27], off offset:1024
	global_load_dwordx4 v[136:139], v[26:27], off offset:2048
	global_load_dwordx4 v[140:143], v[26:27], off offset:3072
	s_add_u32 s1, s0, 0x0
	s_sub_u32 s9, s1, 2048
	s_lshr_b32 s9, s9, 11
	s_cmp_lt_u32 s1, 4096
	s_cselect_b32 s9, 0, s9
	s_mul_i32 s9, s9, 0x6000
	s_add_u32 s18, s10, s9
	s_addc_u32 s19, s11, 0
	s_add_u32 s20, s18, 0x0
	s_addc_u32 s21, s19, 0
	s_add_u32 s18, s18, 0x1000
	s_addc_u32 s19, s19, 0
	global_load_dwordx4 v[144:147], v228, s[18:19]
	global_load_dwordx4 v[148:151], v228, s[18:19] offset:1024
	global_load_dwordx4 v[152:155], v228, s[18:19] offset:2048
	global_load_dwordx4 v[156:159], v228, s[18:19] offset:3072
	global_load_dwordx4 v[160:163], v228, s[20:21]
	global_load_dwordx4 v[164:167], v228, s[20:21] offset:1024
	global_load_dwordx4 v[168:171], v228, s[20:21] offset:2048
	global_load_dwordx4 v[172:175], v228, s[20:21] offset:3072
	s_add_u32 s1, s0, 0x800
	s_sub_u32 s9, s1, 2048
	s_lshr_b32 s9, s9, 11
	s_cmp_lt_u32 s1, 4096
	s_cselect_b32 s9, 0, s9
	s_mul_i32 s9, s9, 0x6000
	s_add_u32 s18, s10, s9
	s_addc_u32 s19, s11, 0
	s_add_u32 s20, s18, 0x0
	s_addc_u32 s21, s19, 0
	s_add_u32 s18, s18, 0x1000
	s_addc_u32 s19, s19, 0
	global_load_dwordx4 v[176:179], v228, s[18:19]
	global_load_dwordx4 v[180:183], v228, s[18:19] offset:1024
	global_load_dwordx4 v[184:187], v228, s[18:19] offset:2048
	global_load_dwordx4 v[188:191], v228, s[18:19] offset:3072
	global_load_dwordx4 v[192:195], v228, s[20:21]
	global_load_dwordx4 v[196:199], v228, s[20:21] offset:1024
	global_load_dwordx4 v[200:203], v228, s[20:21] offset:2048
	global_load_dwordx4 v[204:207], v228, s[20:21] offset:3072
	s_waitcnt vmcnt(20)
	v_mul_f32_e32 v212, v65, v65
	v_fmac_f32_e32 v212, v64, v64
	v_fmac_f32_e32 v212, v66, v66
	v_fmac_f32_e32 v212, v67, v67
	v_mul_f32_e32 v213, v69, v69
	v_fmac_f32_e32 v213, v68, v68
	v_fmac_f32_e32 v213, v70, v70
	v_fmac_f32_e32 v213, v71, v71
	v_mul_f32_e32 v214, v73, v73
	v_fmac_f32_e32 v214, v72, v72
	v_fmac_f32_e32 v214, v74, v74
	v_fmac_f32_e32 v214, v75, v75
	v_mul_f32_e32 v215, v77, v77
	v_fmac_f32_e32 v215, v76, v76
	v_fmac_f32_e32 v215, v78, v78
	v_fmac_f32_e32 v215, v79, v79
	v_add_f32_e32 v208, v212, v213
	v_add_f32_e32 v208, v208, v214
	v_add_f32_e32 v208, v208, v215
	v_mul_f32_e32 v212, v81, v81
	v_fmac_f32_e32 v212, v80, v80
	v_fmac_f32_e32 v212, v82, v82
	v_fmac_f32_e32 v212, v83, v83
	v_mul_f32_e32 v213, v85, v85
	v_fmac_f32_e32 v213, v84, v84
	v_fmac_f32_e32 v213, v86, v86
	v_fmac_f32_e32 v213, v87, v87
	v_mul_f32_e32 v214, v89, v89
	v_fmac_f32_e32 v214, v88, v88
	v_fmac_f32_e32 v214, v90, v90
	v_fmac_f32_e32 v214, v91, v91
	v_mul_f32_e32 v215, v93, v93
	v_fmac_f32_e32 v215, v92, v92
	v_fmac_f32_e32 v215, v94, v94
	v_fmac_f32_e32 v215, v95, v95
	v_add_f32_e32 v209, v212, v213
	v_add_f32_e32 v209, v209, v214
	v_add_f32_e32 v209, v209, v215
	v_mul_f32_e32 v212, v97, v97
	v_fmac_f32_e32 v212, v96, v96
	v_fmac_f32_e32 v212, v98, v98
	v_fmac_f32_e32 v212, v99, v99
	v_mul_f32_e32 v213, v101, v101
	v_fmac_f32_e32 v213, v100, v100
	v_fmac_f32_e32 v213, v102, v102
	v_fmac_f32_e32 v213, v103, v103
	v_mul_f32_e32 v214, v105, v105
	v_fmac_f32_e32 v214, v104, v104
	v_fmac_f32_e32 v214, v106, v106
	v_fmac_f32_e32 v214, v107, v107
	v_mul_f32_e32 v215, v109, v109
	v_fmac_f32_e32 v215, v108, v108
	v_fmac_f32_e32 v215, v110, v110
	v_fmac_f32_e32 v215, v111, v111
	v_add_f32_e32 v210, v212, v213
	v_add_f32_e32 v210, v210, v214
	v_add_f32_e32 v210, v210, v215
	v_mul_f32_e32 v212, v113, v113
	v_fmac_f32_e32 v212, v112, v112
	v_fmac_f32_e32 v212, v114, v114
	v_fmac_f32_e32 v212, v115, v115
	v_mul_f32_e32 v213, v117, v117
	v_fmac_f32_e32 v213, v116, v116
	v_fmac_f32_e32 v213, v118, v118
	v_fmac_f32_e32 v213, v119, v119
	v_mul_f32_e32 v214, v121, v121
	v_fmac_f32_e32 v214, v120, v120
	v_fmac_f32_e32 v214, v122, v122
	v_fmac_f32_e32 v214, v123, v123
	v_mul_f32_e32 v215, v125, v125
	v_fmac_f32_e32 v215, v124, v124
	v_fmac_f32_e32 v215, v126, v126
	v_fmac_f32_e32 v215, v127, v127
	v_add_f32_e32 v211, v212, v213
	v_add_f32_e32 v211, v211, v214
	v_add_f32_e32 v211, v211, v215
	ds_bpermute_b32 v212, v37, v208
	ds_bpermute_b32 v213, v37, v209
	ds_bpermute_b32 v214, v37, v210
	ds_bpermute_b32 v215, v37, v211
	s_waitcnt lgkmcnt(0)
	v_add_f32_e32 v208, v208, v212
	v_add_f32_e32 v209, v209, v213
	v_add_f32_e32 v210, v210, v214
	v_add_f32_e32 v211, v211, v215
	ds_bpermute_b32 v212, v44, v208
	ds_bpermute_b32 v213, v44, v209
	ds_bpermute_b32 v214, v44, v210
	ds_bpermute_b32 v215, v44, v211
	s_waitcnt lgkmcnt(0)
	v_add_f32_e32 v208, v208, v212
	v_add_f32_e32 v209, v209, v213
	v_add_f32_e32 v210, v210, v214
	v_add_f32_e32 v211, v211, v215
	ds_bpermute_b32 v212, v45, v208
	ds_bpermute_b32 v213, v45, v209
	ds_bpermute_b32 v214, v45, v210
	ds_bpermute_b32 v215, v45, v211
	s_waitcnt lgkmcnt(0)
	v_add_f32_e32 v208, v208, v212
	v_add_f32_e32 v209, v209, v213
	v_add_f32_e32 v210, v210, v214
	v_add_f32_e32 v211, v211, v215
	ds_bpermute_b32 v212, v46, v208
	ds_bpermute_b32 v213, v46, v209
	ds_bpermute_b32 v214, v46, v210
	ds_bpermute_b32 v215, v46, v211
	s_waitcnt lgkmcnt(0)
	v_add_f32_e32 v208, v208, v212
	v_add_f32_e32 v209, v209, v213
	v_add_f32_e32 v210, v210, v214
	v_add_f32_e32 v211, v211, v215
	ds_bpermute_b32 v212, v47, v208
	ds_bpermute_b32 v213, v47, v209
	ds_bpermute_b32 v214, v47, v210
	ds_bpermute_b32 v215, v47, v211
	s_waitcnt lgkmcnt(0)
	v_add_f32_e32 v208, v208, v212
	v_add_f32_e32 v209, v209, v213
	v_add_f32_e32 v210, v210, v214
	v_add_f32_e32 v211, v211, v215
	ds_bpermute_b32 v212, v48, v208
	ds_bpermute_b32 v213, v48, v209
	ds_bpermute_b32 v214, v48, v210
	ds_bpermute_b32 v215, v48, v211
	s_waitcnt lgkmcnt(0)
	v_add_f32_e32 v208, v208, v212
	v_add_f32_e32 v209, v209, v213
	v_add_f32_e32 v210, v210, v214
	v_add_f32_e32 v211, v211, v215
	v_fmamk_f32 v208, v208, 0x3a800000, v230
	v_cmp_gt_f32_e32 vcc, s92, v208
	v_mul_f32_e32 v212, 0x4b800000, v208
	s_nop 1
	v_cndmask_b32_e32 v208, v208, v212, vcc
	v_rsq_f32_e32 v208, v208
	s_nop 0
	v_mul_f32_e32 v212, 0x45800000, v208
	v_cndmask_b32_e32 v208, v208, v212, vcc
	v_fmamk_f32 v209, v209, 0x3a800000, v230
	v_cmp_gt_f32_e32 vcc, s92, v209
	v_mul_f32_e32 v212, 0x4b800000, v209
	s_nop 1
	v_cndmask_b32_e32 v209, v209, v212, vcc
	v_rsq_f32_e32 v209, v209
	s_nop 0
	v_mul_f32_e32 v212, 0x45800000, v209
	v_cndmask_b32_e32 v209, v209, v212, vcc
	v_fmamk_f32 v210, v210, 0x3a800000, v230
	v_cmp_gt_f32_e32 vcc, s92, v210
	v_mul_f32_e32 v212, 0x4b800000, v210
	s_nop 1
	v_cndmask_b32_e32 v210, v210, v212, vcc
	v_rsq_f32_e32 v210, v210
	s_nop 0
	v_mul_f32_e32 v212, 0x45800000, v210
	v_cndmask_b32_e32 v210, v210, v212, vcc
	v_fmamk_f32 v211, v211, 0x3a800000, v230
	v_cmp_gt_f32_e32 vcc, s92, v211
	v_mul_f32_e32 v212, 0x4b800000, v211
	s_nop 1
	v_cndmask_b32_e32 v211, v211, v212, vcc
	v_rsq_f32_e32 v211, v211
	s_nop 0
	v_mul_f32_e32 v212, 0x45800000, v211
	v_cndmask_b32_e32 v211, v211, v212, vcc
	s_lshl_b32 s14, s0, 11
	s_mov_b32 s15, 0
	s_waitcnt vmcnt(8)
	v_lshl_add_u64 v[62:63], v[28:29], 0, s[14:15]
	v_mul_f32_e32 v64, v64, v208
	v_mul_f32_e32 v64, v128, v64
	v_add_f32_e32 v216, 1.0, v144
	v_fma_f32 v64, v216, v64, v160
	v_mul_f32_e32 v65, v65, v208
	v_mul_f32_e32 v65, v129, v65
	v_add_f32_e32 v217, 1.0, v145
	v_fma_f32 v65, v217, v65, v161
	v_mul_f32_e32 v66, v66, v208
	v_mul_f32_e32 v66, v130, v66
	v_add_f32_e32 v218, 1.0, v146
	v_fma_f32 v66, v218, v66, v162
	v_mul_f32_e32 v67, v67, v208
	v_mul_f32_e32 v67, v131, v67
	v_add_f32_e32 v219, 1.0, v147
	v_fma_f32 v67, v219, v67, v163
	v_bfe_u32 v220, v64, 16, 1
	v_add3_u32 v64, v64, v220, s89
	v_bfe_u32 v221, v65, 16, 1
	v_add3_u32 v65, v65, v221, s89
	v_bfe_u32 v222, v66, 16, 1
	v_add3_u32 v66, v66, v222, s89
	v_bfe_u32 v223, v67, 16, 1
	v_add3_u32 v67, v67, v223, s89
	v_perm_b32 v64, v65, v64, s88
	v_perm_b32 v65, v67, v66, s88
	global_store_dwordx2 v[62:63], v[64:65], off
	v_mul_f32_e32 v68, v68, v208
	v_mul_f32_e32 v68, v132, v68
	v_add_f32_e32 v216, 1.0, v148
	v_fma_f32 v68, v216, v68, v164
	v_mul_f32_e32 v69, v69, v208
	v_mul_f32_e32 v69, v133, v69
	v_add_f32_e32 v217, 1.0, v149
	v_fma_f32 v69, v217, v69, v165
	v_mul_f32_e32 v70, v70, v208
	v_mul_f32_e32 v70, v134, v70
	v_add_f32_e32 v218, 1.0, v150
	v_fma_f32 v70, v218, v70, v166
	v_mul_f32_e32 v71, v71, v208
	v_mul_f32_e32 v71, v135, v71
	v_add_f32_e32 v219, 1.0, v151
	v_fma_f32 v71, v219, v71, v167
	v_bfe_u32 v220, v68, 16, 1
	v_add3_u32 v68, v68, v220, s89
	v_bfe_u32 v221, v69, 16, 1
	v_add3_u32 v69, v69, v221, s89
	v_bfe_u32 v222, v70, 16, 1
	v_add3_u32 v70, v70, v222, s89
	v_bfe_u32 v223, v71, 16, 1
	v_add3_u32 v71, v71, v223, s89
	v_perm_b32 v68, v69, v68, s88
	v_perm_b32 v69, v71, v70, s88
	global_store_dwordx2 v[62:63], v[68:69], off offset:512
	v_mul_f32_e32 v72, v72, v208
	v_mul_f32_e32 v72, v136, v72
	v_add_f32_e32 v216, 1.0, v152
	v_fma_f32 v72, v216, v72, v168
	v_mul_f32_e32 v73, v73, v208
	v_mul_f32_e32 v73, v137, v73
	v_add_f32_e32 v217, 1.0, v153
	v_fma_f32 v73, v217, v73, v169
	v_mul_f32_e32 v74, v74, v208
	v_mul_f32_e32 v74, v138, v74
	v_add_f32_e32 v218, 1.0, v154
	v_fma_f32 v74, v218, v74, v170
	v_mul_f32_e32 v75, v75, v208
	v_mul_f32_e32 v75, v139, v75
	v_add_f32_e32 v219, 1.0, v155
	v_fma_f32 v75, v219, v75, v171
	v_bfe_u32 v220, v72, 16, 1
	v_add3_u32 v72, v72, v220, s89
	v_bfe_u32 v221, v73, 16, 1
	v_add3_u32 v73, v73, v221, s89
	v_bfe_u32 v222, v74, 16, 1
	v_add3_u32 v74, v74, v222, s89
	v_bfe_u32 v223, v75, 16, 1
	v_add3_u32 v75, v75, v223, s89
	v_perm_b32 v72, v73, v72, s88
	v_perm_b32 v73, v75, v74, s88
	global_store_dwordx2 v[62:63], v[72:73], off offset:1024
	v_mul_f32_e32 v76, v76, v208
	v_mul_f32_e32 v76, v140, v76
	v_add_f32_e32 v216, 1.0, v156
	v_fma_f32 v76, v216, v76, v172
	v_mul_f32_e32 v77, v77, v208
	v_mul_f32_e32 v77, v141, v77
	v_add_f32_e32 v217, 1.0, v157
	v_fma_f32 v77, v217, v77, v173
	v_mul_f32_e32 v78, v78, v208
	v_mul_f32_e32 v78, v142, v78
	v_add_f32_e32 v218, 1.0, v158
	v_fma_f32 v78, v218, v78, v174
	v_mul_f32_e32 v79, v79, v208
	v_mul_f32_e32 v79, v143, v79
	v_add_f32_e32 v219, 1.0, v159
	v_fma_f32 v79, v219, v79, v175
	v_bfe_u32 v220, v76, 16, 1
	v_add3_u32 v76, v76, v220, s89
	v_bfe_u32 v221, v77, 16, 1
	v_add3_u32 v77, v77, v221, s89
	v_bfe_u32 v222, v78, 16, 1
	v_add3_u32 v78, v78, v222, s89
	v_bfe_u32 v223, v79, 16, 1
	v_add3_u32 v79, v79, v223, s89
	v_perm_b32 v76, v77, v76, s88
	v_perm_b32 v77, v79, v78, s88
	global_store_dwordx2 v[62:63], v[76:77], off offset:1536
	s_add_u32 s1, s0, 0x1000
	s_sub_u32 s9, s1, 2048
	s_lshr_b32 s9, s9, 11
	s_cmp_lt_u32 s1, 4096
	s_cselect_b32 s9, 0, s9
	s_mul_i32 s9, s9, 0x6000
	s_add_u32 s18, s10, s9
	s_addc_u32 s19, s11, 0
	s_add_u32 s20, s18, 0x0
	s_addc_u32 s21, s19, 0
	s_add_u32 s18, s18, 0x1000
	s_addc_u32 s19, s19, 0
	global_load_dwordx4 v[144:147], v228, s[18:19]
	global_load_dwordx4 v[148:151], v228, s[18:19] offset:1024
	global_load_dwordx4 v[152:155], v228, s[18:19] offset:2048
	global_load_dwordx4 v[156:159], v228, s[18:19] offset:3072
	global_load_dwordx4 v[160:163], v228, s[20:21]
	global_load_dwordx4 v[164:167], v228, s[20:21] offset:1024
	global_load_dwordx4 v[168:171], v228, s[20:21] offset:2048
	global_load_dwordx4 v[172:175], v228, s[20:21] offset:3072
	s_add_u32 s14, s14, 0x400000
	s_waitcnt vmcnt(12)
	v_lshl_add_u64 v[62:63], v[28:29], 0, s[14:15]
	v_mul_f32_e32 v80, v80, v209
	v_mul_f32_e32 v80, v128, v80
	v_add_f32_e32 v216, 1.0, v176
	v_fma_f32 v80, v216, v80, v192
	v_mul_f32_e32 v81, v81, v209
	v_mul_f32_e32 v81, v129, v81
	v_add_f32_e32 v217, 1.0, v177
	v_fma_f32 v81, v217, v81, v193
	v_mul_f32_e32 v82, v82, v209
	v_mul_f32_e32 v82, v130, v82
	v_add_f32_e32 v218, 1.0, v178
	v_fma_f32 v82, v218, v82, v194
	v_mul_f32_e32 v83, v83, v209
	v_mul_f32_e32 v83, v131, v83
	v_add_f32_e32 v219, 1.0, v179
	v_fma_f32 v83, v219, v83, v195
	v_bfe_u32 v220, v80, 16, 1
	v_add3_u32 v80, v80, v220, s89
	v_bfe_u32 v221, v81, 16, 1
	v_add3_u32 v81, v81, v221, s89
	v_bfe_u32 v222, v82, 16, 1
	v_add3_u32 v82, v82, v222, s89
	v_bfe_u32 v223, v83, 16, 1
	v_add3_u32 v83, v83, v223, s89
	v_perm_b32 v80, v81, v80, s88
	v_perm_b32 v81, v83, v82, s88
	global_store_dwordx2 v[62:63], v[80:81], off
	v_mul_f32_e32 v84, v84, v209
	v_mul_f32_e32 v84, v132, v84
	v_add_f32_e32 v216, 1.0, v180
	v_fma_f32 v84, v216, v84, v196
	v_mul_f32_e32 v85, v85, v209
	v_mul_f32_e32 v85, v133, v85
	v_add_f32_e32 v217, 1.0, v181
	v_fma_f32 v85, v217, v85, v197
	v_mul_f32_e32 v86, v86, v209
	v_mul_f32_e32 v86, v134, v86
	v_add_f32_e32 v218, 1.0, v182
	v_fma_f32 v86, v218, v86, v198
	v_mul_f32_e32 v87, v87, v209
	v_mul_f32_e32 v87, v135, v87
	v_add_f32_e32 v219, 1.0, v183
	v_fma_f32 v87, v219, v87, v199
	v_bfe_u32 v220, v84, 16, 1
	v_add3_u32 v84, v84, v220, s89
	v_bfe_u32 v221, v85, 16, 1
	v_add3_u32 v85, v85, v221, s89
	v_bfe_u32 v222, v86, 16, 1
	v_add3_u32 v86, v86, v222, s89
	v_bfe_u32 v223, v87, 16, 1
	v_add3_u32 v87, v87, v223, s89
	v_perm_b32 v84, v85, v84, s88
	v_perm_b32 v85, v87, v86, s88
	global_store_dwordx2 v[62:63], v[84:85], off offset:512
	v_mul_f32_e32 v88, v88, v209
	v_mul_f32_e32 v88, v136, v88
	v_add_f32_e32 v216, 1.0, v184
	v_fma_f32 v88, v216, v88, v200
	v_mul_f32_e32 v89, v89, v209
	v_mul_f32_e32 v89, v137, v89
	v_add_f32_e32 v217, 1.0, v185
	v_fma_f32 v89, v217, v89, v201
	v_mul_f32_e32 v90, v90, v209
	v_mul_f32_e32 v90, v138, v90
	v_add_f32_e32 v218, 1.0, v186
	v_fma_f32 v90, v218, v90, v202
	v_mul_f32_e32 v91, v91, v209
	v_mul_f32_e32 v91, v139, v91
	v_add_f32_e32 v219, 1.0, v187
	v_fma_f32 v91, v219, v91, v203
	v_bfe_u32 v220, v88, 16, 1
	v_add3_u32 v88, v88, v220, s89
	v_bfe_u32 v221, v89, 16, 1
	v_add3_u32 v89, v89, v221, s89
	v_bfe_u32 v222, v90, 16, 1
	v_add3_u32 v90, v90, v222, s89
	v_bfe_u32 v223, v91, 16, 1
	v_add3_u32 v91, v91, v223, s89
	v_perm_b32 v88, v89, v88, s88
	v_perm_b32 v89, v91, v90, s88
	global_store_dwordx2 v[62:63], v[88:89], off offset:1024
	v_mul_f32_e32 v92, v92, v209
	v_mul_f32_e32 v92, v140, v92
	v_add_f32_e32 v216, 1.0, v188
	v_fma_f32 v92, v216, v92, v204
	v_mul_f32_e32 v93, v93, v209
	v_mul_f32_e32 v93, v141, v93
	v_add_f32_e32 v217, 1.0, v189
	v_fma_f32 v93, v217, v93, v205
	v_mul_f32_e32 v94, v94, v209
	v_mul_f32_e32 v94, v142, v94
	v_add_f32_e32 v218, 1.0, v190
	v_fma_f32 v94, v218, v94, v206
	v_mul_f32_e32 v95, v95, v209
	v_mul_f32_e32 v95, v143, v95
	v_add_f32_e32 v219, 1.0, v191
	v_fma_f32 v95, v219, v95, v207
	v_bfe_u32 v220, v92, 16, 1
	v_add3_u32 v92, v92, v220, s89
	v_bfe_u32 v221, v93, 16, 1
	v_add3_u32 v93, v93, v221, s89
	v_bfe_u32 v222, v94, 16, 1
	v_add3_u32 v94, v94, v222, s89
	v_bfe_u32 v223, v95, 16, 1
	v_add3_u32 v95, v95, v223, s89
	v_perm_b32 v92, v93, v92, s88
	v_perm_b32 v93, v95, v94, s88
	global_store_dwordx2 v[62:63], v[92:93], off offset:1536
	s_add_u32 s1, s0, 0x1800
	s_sub_u32 s9, s1, 2048
	s_lshr_b32 s9, s9, 11
	s_cmp_lt_u32 s1, 4096
	s_cselect_b32 s9, 0, s9
	s_mul_i32 s9, s9, 0x6000
	s_add_u32 s18, s10, s9
	s_addc_u32 s19, s11, 0
	s_add_u32 s20, s18, 0x0
	s_addc_u32 s21, s19, 0
	s_add_u32 s18, s18, 0x1000
	s_addc_u32 s19, s19, 0
	global_load_dwordx4 v[176:179], v228, s[18:19]
	global_load_dwordx4 v[180:183], v228, s[18:19] offset:1024
	global_load_dwordx4 v[184:187], v228, s[18:19] offset:2048
	global_load_dwordx4 v[188:191], v228, s[18:19] offset:3072
	global_load_dwordx4 v[192:195], v228, s[20:21]
	global_load_dwordx4 v[196:199], v228, s[20:21] offset:1024
	global_load_dwordx4 v[200:203], v228, s[20:21] offset:2048
	global_load_dwordx4 v[204:207], v228, s[20:21] offset:3072
	s_add_u32 s14, s14, 0x400000
	s_waitcnt vmcnt(12)
	v_lshl_add_u64 v[62:63], v[28:29], 0, s[14:15]
	v_mul_f32_e32 v96, v96, v210
	v_mul_f32_e32 v96, v128, v96
	v_add_f32_e32 v216, 1.0, v144
	v_fma_f32 v96, v216, v96, v160
	v_mul_f32_e32 v97, v97, v210
	v_mul_f32_e32 v97, v129, v97
	v_add_f32_e32 v217, 1.0, v145
	v_fma_f32 v97, v217, v97, v161
	v_mul_f32_e32 v98, v98, v210
	v_mul_f32_e32 v98, v130, v98
	v_add_f32_e32 v218, 1.0, v146
	v_fma_f32 v98, v218, v98, v162
	v_mul_f32_e32 v99, v99, v210
	v_mul_f32_e32 v99, v131, v99
	v_add_f32_e32 v219, 1.0, v147
	v_fma_f32 v99, v219, v99, v163
	v_bfe_u32 v220, v96, 16, 1
	v_add3_u32 v96, v96, v220, s89
	v_bfe_u32 v221, v97, 16, 1
	v_add3_u32 v97, v97, v221, s89
	v_bfe_u32 v222, v98, 16, 1
	v_add3_u32 v98, v98, v222, s89
	v_bfe_u32 v223, v99, 16, 1
	v_add3_u32 v99, v99, v223, s89
	v_perm_b32 v96, v97, v96, s88
	v_perm_b32 v97, v99, v98, s88
	global_store_dwordx2 v[62:63], v[96:97], off
	v_mul_f32_e32 v100, v100, v210
	v_mul_f32_e32 v100, v132, v100
	v_add_f32_e32 v216, 1.0, v148
	v_fma_f32 v100, v216, v100, v164
	v_mul_f32_e32 v101, v101, v210
	v_mul_f32_e32 v101, v133, v101
	v_add_f32_e32 v217, 1.0, v149
	v_fma_f32 v101, v217, v101, v165
	v_mul_f32_e32 v102, v102, v210
	v_mul_f32_e32 v102, v134, v102
	v_add_f32_e32 v218, 1.0, v150
	v_fma_f32 v102, v218, v102, v166
	v_mul_f32_e32 v103, v103, v210
	v_mul_f32_e32 v103, v135, v103
	v_add_f32_e32 v219, 1.0, v151
	v_fma_f32 v103, v219, v103, v167
	v_bfe_u32 v220, v100, 16, 1
	v_add3_u32 v100, v100, v220, s89
	v_bfe_u32 v221, v101, 16, 1
	v_add3_u32 v101, v101, v221, s89
	v_bfe_u32 v222, v102, 16, 1
	v_add3_u32 v102, v102, v222, s89
	v_bfe_u32 v223, v103, 16, 1
	v_add3_u32 v103, v103, v223, s89
	v_perm_b32 v100, v101, v100, s88
	v_perm_b32 v101, v103, v102, s88
	global_store_dwordx2 v[62:63], v[100:101], off offset:512
	v_mul_f32_e32 v104, v104, v210
	v_mul_f32_e32 v104, v136, v104
	v_add_f32_e32 v216, 1.0, v152
	v_fma_f32 v104, v216, v104, v168
	v_mul_f32_e32 v105, v105, v210
	v_mul_f32_e32 v105, v137, v105
	v_add_f32_e32 v217, 1.0, v153
	v_fma_f32 v105, v217, v105, v169
	v_mul_f32_e32 v106, v106, v210
	v_mul_f32_e32 v106, v138, v106
	v_add_f32_e32 v218, 1.0, v154
	v_fma_f32 v106, v218, v106, v170
	v_mul_f32_e32 v107, v107, v210
	v_mul_f32_e32 v107, v139, v107
	v_add_f32_e32 v219, 1.0, v155
	v_fma_f32 v107, v219, v107, v171
	v_bfe_u32 v220, v104, 16, 1
	v_add3_u32 v104, v104, v220, s89
	v_bfe_u32 v221, v105, 16, 1
	v_add3_u32 v105, v105, v221, s89
	v_bfe_u32 v222, v106, 16, 1
	v_add3_u32 v106, v106, v222, s89
	v_bfe_u32 v223, v107, 16, 1
	v_add3_u32 v107, v107, v223, s89
	v_perm_b32 v104, v105, v104, s88
	v_perm_b32 v105, v107, v106, s88
	global_store_dwordx2 v[62:63], v[104:105], off offset:1024
	v_mul_f32_e32 v108, v108, v210
	v_mul_f32_e32 v108, v140, v108
	v_add_f32_e32 v216, 1.0, v156
	v_fma_f32 v108, v216, v108, v172
	v_mul_f32_e32 v109, v109, v210
	v_mul_f32_e32 v109, v141, v109
	v_add_f32_e32 v217, 1.0, v157
	v_fma_f32 v109, v217, v109, v173
	v_mul_f32_e32 v110, v110, v210
	v_mul_f32_e32 v110, v142, v110
	v_add_f32_e32 v218, 1.0, v158
	v_fma_f32 v110, v218, v110, v174
	v_mul_f32_e32 v111, v111, v210
	v_mul_f32_e32 v111, v143, v111
	v_add_f32_e32 v219, 1.0, v159
	v_fma_f32 v111, v219, v111, v175
	v_bfe_u32 v220, v108, 16, 1
	v_add3_u32 v108, v108, v220, s89
	v_bfe_u32 v221, v109, 16, 1
	v_add3_u32 v109, v109, v221, s89
	v_bfe_u32 v222, v110, 16, 1
	v_add3_u32 v110, v110, v222, s89
	v_bfe_u32 v223, v111, 16, 1
	v_add3_u32 v111, v111, v223, s89
	v_perm_b32 v108, v109, v108, s88
	v_perm_b32 v109, v111, v110, s88
	global_store_dwordx2 v[62:63], v[108:109], off offset:1536
	s_add_u32 s14, s14, 0x400000
	s_waitcnt vmcnt(4)
	v_lshl_add_u64 v[62:63], v[28:29], 0, s[14:15]
	v_mul_f32_e32 v112, v112, v211
	v_mul_f32_e32 v112, v128, v112
	v_add_f32_e32 v216, 1.0, v176
	v_fma_f32 v112, v216, v112, v192
	v_mul_f32_e32 v113, v113, v211
	v_mul_f32_e32 v113, v129, v113
	v_add_f32_e32 v217, 1.0, v177
	v_fma_f32 v113, v217, v113, v193
	v_mul_f32_e32 v114, v114, v211
	v_mul_f32_e32 v114, v130, v114
	v_add_f32_e32 v218, 1.0, v178
	v_fma_f32 v114, v218, v114, v194
	v_mul_f32_e32 v115, v115, v211
	v_mul_f32_e32 v115, v131, v115
	v_add_f32_e32 v219, 1.0, v179
	v_fma_f32 v115, v219, v115, v195
	v_bfe_u32 v220, v112, 16, 1
	v_add3_u32 v112, v112, v220, s89
	v_bfe_u32 v221, v113, 16, 1
	v_add3_u32 v113, v113, v221, s89
	v_bfe_u32 v222, v114, 16, 1
	v_add3_u32 v114, v114, v222, s89
	v_bfe_u32 v223, v115, 16, 1
	v_add3_u32 v115, v115, v223, s89
	v_perm_b32 v112, v113, v112, s88
	v_perm_b32 v113, v115, v114, s88
	global_store_dwordx2 v[62:63], v[112:113], off
	v_mul_f32_e32 v116, v116, v211
	v_mul_f32_e32 v116, v132, v116
	v_add_f32_e32 v216, 1.0, v180
	v_fma_f32 v116, v216, v116, v196
	v_mul_f32_e32 v117, v117, v211
	v_mul_f32_e32 v117, v133, v117
	v_add_f32_e32 v217, 1.0, v181
	v_fma_f32 v117, v217, v117, v197
	v_mul_f32_e32 v118, v118, v211
	v_mul_f32_e32 v118, v134, v118
	v_add_f32_e32 v218, 1.0, v182
	v_fma_f32 v118, v218, v118, v198
	v_mul_f32_e32 v119, v119, v211
	v_mul_f32_e32 v119, v135, v119
	v_add_f32_e32 v219, 1.0, v183
	v_fma_f32 v119, v219, v119, v199
	v_bfe_u32 v220, v116, 16, 1
	v_add3_u32 v116, v116, v220, s89
	v_bfe_u32 v221, v117, 16, 1
	v_add3_u32 v117, v117, v221, s89
	v_bfe_u32 v222, v118, 16, 1
	v_add3_u32 v118, v118, v222, s89
	v_bfe_u32 v223, v119, 16, 1
	v_add3_u32 v119, v119, v223, s89
	v_perm_b32 v116, v117, v116, s88
	v_perm_b32 v117, v119, v118, s88
	global_store_dwordx2 v[62:63], v[116:117], off offset:512
	v_mul_f32_e32 v120, v120, v211
	v_mul_f32_e32 v120, v136, v120
	v_add_f32_e32 v216, 1.0, v184
	v_fma_f32 v120, v216, v120, v200
	v_mul_f32_e32 v121, v121, v211
	v_mul_f32_e32 v121, v137, v121
	v_add_f32_e32 v217, 1.0, v185
	v_fma_f32 v121, v217, v121, v201
	v_mul_f32_e32 v122, v122, v211
	v_mul_f32_e32 v122, v138, v122
	v_add_f32_e32 v218, 1.0, v186
	v_fma_f32 v122, v218, v122, v202
	v_mul_f32_e32 v123, v123, v211
	v_mul_f32_e32 v123, v139, v123
	v_add_f32_e32 v219, 1.0, v187
	v_fma_f32 v123, v219, v123, v203
	v_bfe_u32 v220, v120, 16, 1
	v_add3_u32 v120, v120, v220, s89
	v_bfe_u32 v221, v121, 16, 1
	v_add3_u32 v121, v121, v221, s89
	v_bfe_u32 v222, v122, 16, 1
	v_add3_u32 v122, v122, v222, s89
	v_bfe_u32 v223, v123, 16, 1
	v_add3_u32 v123, v123, v223, s89
	v_perm_b32 v120, v121, v120, s88
	v_perm_b32 v121, v123, v122, s88
	global_store_dwordx2 v[62:63], v[120:121], off offset:1024
	v_mul_f32_e32 v124, v124, v211
	v_mul_f32_e32 v124, v140, v124
	v_add_f32_e32 v216, 1.0, v188
	v_fma_f32 v124, v216, v124, v204
	v_mul_f32_e32 v125, v125, v211
	v_mul_f32_e32 v125, v141, v125
	v_add_f32_e32 v217, 1.0, v189
	v_fma_f32 v125, v217, v125, v205
	v_mul_f32_e32 v126, v126, v211
	v_mul_f32_e32 v126, v142, v126
	v_add_f32_e32 v218, 1.0, v190
	v_fma_f32 v126, v218, v126, v206
	v_mul_f32_e32 v127, v127, v211
	v_mul_f32_e32 v127, v143, v127
	v_add_f32_e32 v219, 1.0, v191
	v_fma_f32 v127, v219, v127, v207
	v_bfe_u32 v220, v124, 16, 1
	v_add3_u32 v124, v124, v220, s89
	v_bfe_u32 v221, v125, 16, 1
	v_add3_u32 v125, v125, v221, s89
	v_bfe_u32 v222, v126, 16, 1
	v_add3_u32 v126, v126, v222, s89
	v_bfe_u32 v223, v127, 16, 1
	v_add3_u32 v127, v127, v223, s89
	v_perm_b32 v124, v125, v124, s88
	v_perm_b32 v125, v127, v126, s88
	global_store_dwordx2 v[62:63], v[124:125], off offset:1536
	s_branch .LBB0_263
	s_branch .LBB0_256

.LBB0_2126:
	s_or_b64 exec, exec, s[0:1]
	v_mov_b32_e32 v8, v231
	s_waitcnt lgkmcnt(0)
	s_barrier
	ds_read_b64 v[4:5], v229 offset:63568
	ds_read_b64 v[2:3], v229 offset:63760
	ds_read_b64 v[0:1], v229 offset:63760
	ds_read_b64 v[6:7], v229 offset:63760
	v_ashrrev_i32_e32 v9, 6, v8
	s_mov_b32 s0, s76
	s_nop 0
	v_lshl_add_u32 v16, s0, 2, v9
	v_cmp_gt_i32_e32 vcc, s94, v16
	s_and_saveexec_b64 s[0:1], vcc
	s_movk_i32 s6, 0xfff
	s_movk_i32 s7, 0x1800
	s_mov_b32 s8, 0x7060302
	s_movk_i32 s9, 0x1fff
	s_cbranch_execz .LBB0_2129
	v_readlane_b32 s2, v255, 29
	v_readlane_b32 s3, v255, 30
	s_lshl_b64 s[2:3], s[2:3], 2
	s_waitcnt lgkmcnt(0)
	v_lshl_add_u64 v[6:7], v[6:7], 0, s[2:3]
	s_mov_b64 s[2:3], 0x2a20000
	v_lshl_add_u64 v[18:19], v[6:7], 0, s[2:3]
	v_and_b32_e32 v7, 64, v244
	v_lshlrev_b32_e32 v6, 2, v8
	v_add_u32_e32 v7, 64, v7
	v_xor_b32_e32 v8, 32, v244
	v_cmp_lt_i32_e32 vcc, v8, v7
	v_readlane_b32 s2, v255, 27
	v_readlane_b32 s3, v255, 28
	v_cndmask_b32_e32 v8, v244, v8, vcc
	v_lshlrev_b32_e32 v35, 2, v8
	v_xor_b32_e32 v8, 16, v244
	v_cmp_lt_i32_e32 vcc, v8, v7
	s_lshl_b64 s[2:3], s[2:3], 2
	v_and_b32_e32 v6, 0xfc, v6
	v_cndmask_b32_e32 v8, v244, v8, vcc
	v_lshlrev_b32_e32 v42, 2, v8
	v_xor_b32_e32 v8, 8, v244
	v_cmp_lt_i32_e32 vcc, v8, v7
	v_lshl_add_u64 v[4:5], v[4:5], 0, s[2:3]
	v_lshlrev_b32_e32 v228, 2, v6
	v_cndmask_b32_e32 v8, v244, v8, vcc
	v_lshlrev_b32_e32 v43, 2, v8
	v_xor_b32_e32 v8, 4, v244
	v_cmp_lt_i32_e32 vcc, v8, v7
	v_lshl_add_u64 v[20:21], v[4:5], 0, v[228:229]
	v_lshl_add_u64 v[2:3], v[2:3], 0, v[228:229]
	v_cndmask_b32_e32 v8, v244, v8, vcc
	v_lshlrev_b32_e32 v44, 2, v8
	v_xor_b32_e32 v8, 2, v244
	v_cmp_lt_i32_e32 vcc, v8, v7
	v_lshlrev_b32_e32 v228, 1, v6
	v_or_b32_e32 v4, 0x100, v6
	v_cndmask_b32_e32 v8, v244, v8, vcc
	v_lshlrev_b32_e32 v45, 2, v8
	v_xor_b32_e32 v8, 1, v244
	v_cmp_lt_i32_e32 vcc, v8, v7
	v_or_b32_e32 v10, 0x300, v6
	v_lshl_add_u64 v[0:1], v[0:1], 0, v[228:229]
	v_cndmask_b32_e32 v7, v244, v8, vcc
	v_or_b32_e32 v8, 0x200, v6
	v_lshlrev_b32_e32 v46, 2, v7
	v_lshl_add_u64 v[22:23], v[2:3], 0, s[56:57]
	v_lshl_add_u64 v[24:25], v[0:1], 0, s[58:59]
	s_mov_b64 s[2:3], 0
	v_lshlrev_b32_e32 v26, 2, v6
	v_lshlrev_b32_e32 v28, 2, v4
	v_lshlrev_b32_e32 v30, 2, v8
	v_lshlrev_b32_e32 v32, 2, v10
	s_cmp_eq_u32 s77, 0x800
	s_cbranch_scc0 .LBB0_2128
	v_readfirstlane_b32 s2, v16
	v_readfirstlane_b32 s10, v18
	v_readfirstlane_b32 s11, v19
	s_lshl_b32 s14, s2, 12
	s_mov_b32 s15, 0
	v_lshl_add_u64 v[60:61], v[22:23], 0, s[14:15]
	global_load_dwordx4 v[64:67], v[60:61], off
	global_load_dwordx4 v[68:71], v[60:61], off offset:1024
	global_load_dwordx4 v[72:75], v[60:61], off offset:2048
	global_load_dwordx4 v[76:79], v[60:61], off offset:3072
	s_add_u32 s14, s14, 0x800000
	v_lshl_add_u64 v[60:61], v[22:23], 0, s[14:15]
	global_load_dwordx4 v[80:83], v[60:61], off
	global_load_dwordx4 v[84:87], v[60:61], off offset:1024
	global_load_dwordx4 v[88:91], v[60:61], off offset:2048
	global_load_dwordx4 v[92:95], v[60:61], off offset:3072
	s_add_u32 s14, s14, 0x800000
	v_lshl_add_u64 v[60:61], v[22:23], 0, s[14:15]
	global_load_dwordx4 v[96:99], v[60:61], off
	global_load_dwordx4 v[100:103], v[60:61], off offset:1024
	global_load_dwordx4 v[104:107], v[60:61], off offset:2048
	global_load_dwordx4 v[108:111], v[60:61], off offset:3072
	s_add_u32 s14, s14, 0x800000
	v_lshl_add_u64 v[60:61], v[22:23], 0, s[14:15]
	global_load_dwordx4 v[112:115], v[60:61], off
	global_load_dwordx4 v[116:119], v[60:61], off offset:1024
	global_load_dwordx4 v[120:123], v[60:61], off offset:2048
	global_load_dwordx4 v[124:127], v[60:61], off offset:3072
	global_load_dwordx4 v[128:131], v[20:21], off
	global_load_dwordx4 v[132:135], v[20:21], off offset:1024
	global_load_dwordx4 v[136:139], v[20:21], off offset:2048
	global_load_dwordx4 v[140:143], v[20:21], off offset:3072
	s_add_u32 s3, s2, 0x0
	s_sub_u32 s5, s3, 2048
	s_lshr_b32 s5, s5, 11
	s_cmp_lt_u32 s3, 4096
	s_cselect_b32 s5, 0, s5
	s_mul_i32 s5, s5, 0x6000
	s_add_u32 s18, s10, s5
	s_addc_u32 s19, s11, 0
	s_add_u32 s20, s18, 0x3000
	s_addc_u32 s21, s19, 0
	s_add_u32 s18, s18, 0x4000
	s_addc_u32 s19, s19, 0
	global_load_dwordx4 v[144:147], v26, s[18:19]
	global_load_dwordx4 v[148:151], v26, s[18:19] offset:1024
	global_load_dwordx4 v[152:155], v26, s[18:19] offset:2048
	global_load_dwordx4 v[156:159], v26, s[18:19] offset:3072
	global_load_dwordx4 v[160:163], v26, s[20:21]
	global_load_dwordx4 v[164:167], v26, s[20:21] offset:1024
	global_load_dwordx4 v[168:171], v26, s[20:21] offset:2048
	global_load_dwordx4 v[172:175], v26, s[20:21] offset:3072
	s_add_u32 s3, s2, 0x800
	s_sub_u32 s5, s3, 2048
	s_lshr_b32 s5, s5, 11
	s_cmp_lt_u32 s3, 4096
	s_cselect_b32 s5, 0, s5
	s_mul_i32 s5, s5, 0x6000
	s_add_u32 s18, s10, s5
	s_addc_u32 s19, s11, 0
	s_add_u32 s20, s18, 0x3000
	s_addc_u32 s21, s19, 0
	s_add_u32 s18, s18, 0x4000
	s_addc_u32 s19, s19, 0
	global_load_dwordx4 v[176:179], v26, s[18:19]
	global_load_dwordx4 v[180:183], v26, s[18:19] offset:1024
	global_load_dwordx4 v[184:187], v26, s[18:19] offset:2048
	global_load_dwordx4 v[188:191], v26, s[18:19] offset:3072
	global_load_dwordx4 v[192:195], v26, s[20:21]
	global_load_dwordx4 v[196:199], v26, s[20:21] offset:1024
	global_load_dwordx4 v[200:203], v26, s[20:21] offset:2048
	global_load_dwordx4 v[204:207], v26, s[20:21] offset:3072
	s_waitcnt vmcnt(20)
	v_mul_f32_e32 v212, v65, v65
	v_fmac_f32_e32 v212, v64, v64
	v_fmac_f32_e32 v212, v66, v66
	v_fmac_f32_e32 v212, v67, v67
	v_mul_f32_e32 v213, v69, v69
	v_fmac_f32_e32 v213, v68, v68
	v_fmac_f32_e32 v213, v70, v70
	v_fmac_f32_e32 v213, v71, v71
	v_mul_f32_e32 v214, v73, v73
	v_fmac_f32_e32 v214, v72, v72
	v_fmac_f32_e32 v214, v74, v74
	v_fmac_f32_e32 v214, v75, v75
	v_mul_f32_e32 v215, v77, v77
	v_fmac_f32_e32 v215, v76, v76
	v_fmac_f32_e32 v215, v78, v78
	v_fmac_f32_e32 v215, v79, v79
	v_add_f32_e32 v208, v212, v213
	v_add_f32_e32 v208, v208, v214
	v_add_f32_e32 v208, v208, v215
	v_mul_f32_e32 v212, v81, v81
	v_fmac_f32_e32 v212, v80, v80
	v_fmac_f32_e32 v212, v82, v82
	v_fmac_f32_e32 v212, v83, v83
	v_mul_f32_e32 v213, v85, v85
	v_fmac_f32_e32 v213, v84, v84
	v_fmac_f32_e32 v213, v86, v86
	v_fmac_f32_e32 v213, v87, v87
	v_mul_f32_e32 v214, v89, v89
	v_fmac_f32_e32 v214, v88, v88
	v_fmac_f32_e32 v214, v90, v90
	v_fmac_f32_e32 v214, v91, v91
	v_mul_f32_e32 v215, v93, v93
	v_fmac_f32_e32 v215, v92, v92
	v_fmac_f32_e32 v215, v94, v94
	v_fmac_f32_e32 v215, v95, v95
	v_add_f32_e32 v209, v212, v213
	v_add_f32_e32 v209, v209, v214
	v_add_f32_e32 v209, v209, v215
	v_mul_f32_e32 v212, v97, v97
	v_fmac_f32_e32 v212, v96, v96
	v_fmac_f32_e32 v212, v98, v98
	v_fmac_f32_e32 v212, v99, v99
	v_mul_f32_e32 v213, v101, v101
	v_fmac_f32_e32 v213, v100, v100
	v_fmac_f32_e32 v213, v102, v102
	v_fmac_f32_e32 v213, v103, v103
	v_mul_f32_e32 v214, v105, v105
	v_fmac_f32_e32 v214, v104, v104
	v_fmac_f32_e32 v214, v106, v106
	v_fmac_f32_e32 v214, v107, v107
	v_mul_f32_e32 v215, v109, v109
	v_fmac_f32_e32 v215, v108, v108
	v_fmac_f32_e32 v215, v110, v110
	v_fmac_f32_e32 v215, v111, v111
	v_add_f32_e32 v210, v212, v213
	v_add_f32_e32 v210, v210, v214
	v_add_f32_e32 v210, v210, v215
	v_mul_f32_e32 v212, v113, v113
	v_fmac_f32_e32 v212, v112, v112
	v_fmac_f32_e32 v212, v114, v114
	v_fmac_f32_e32 v212, v115, v115
	v_mul_f32_e32 v213, v117, v117
	v_fmac_f32_e32 v213, v116, v116
	v_fmac_f32_e32 v213, v118, v118
	v_fmac_f32_e32 v213, v119, v119
	v_mul_f32_e32 v214, v121, v121
	v_fmac_f32_e32 v214, v120, v120
	v_fmac_f32_e32 v214, v122, v122
	v_fmac_f32_e32 v214, v123, v123
	v_mul_f32_e32 v215, v125, v125
	v_fmac_f32_e32 v215, v124, v124
	v_fmac_f32_e32 v215, v126, v126
	v_fmac_f32_e32 v215, v127, v127
	v_add_f32_e32 v211, v212, v213
	v_add_f32_e32 v211, v211, v214
	v_add_f32_e32 v211, v211, v215
	ds_bpermute_b32 v212, v35, v208
	ds_bpermute_b32 v213, v35, v209
	ds_bpermute_b32 v214, v35, v210
	ds_bpermute_b32 v215, v35, v211
	s_waitcnt lgkmcnt(0)
	v_add_f32_e32 v208, v208, v212
	v_add_f32_e32 v209, v209, v213
	v_add_f32_e32 v210, v210, v214
	v_add_f32_e32 v211, v211, v215
	ds_bpermute_b32 v212, v42, v208
	ds_bpermute_b32 v213, v42, v209
	ds_bpermute_b32 v214, v42, v210
	ds_bpermute_b32 v215, v42, v211
	s_waitcnt lgkmcnt(0)
	v_add_f32_e32 v208, v208, v212
	v_add_f32_e32 v209, v209, v213
	v_add_f32_e32 v210, v210, v214
	v_add_f32_e32 v211, v211, v215
	ds_bpermute_b32 v212, v43, v208
	ds_bpermute_b32 v213, v43, v209
	ds_bpermute_b32 v214, v43, v210
	ds_bpermute_b32 v215, v43, v211
	s_waitcnt lgkmcnt(0)
	v_add_f32_e32 v208, v208, v212
	v_add_f32_e32 v209, v209, v213
	v_add_f32_e32 v210, v210, v214
	v_add_f32_e32 v211, v211, v215
	ds_bpermute_b32 v212, v44, v208
	ds_bpermute_b32 v213, v44, v209
	ds_bpermute_b32 v214, v44, v210
	ds_bpermute_b32 v215, v44, v211
	s_waitcnt lgkmcnt(0)
	v_add_f32_e32 v208, v208, v212
	v_add_f32_e32 v209, v209, v213
	v_add_f32_e32 v210, v210, v214
	v_add_f32_e32 v211, v211, v215
	ds_bpermute_b32 v212, v45, v208
	ds_bpermute_b32 v213, v45, v209
	ds_bpermute_b32 v214, v45, v210
	ds_bpermute_b32 v215, v45, v211
	s_waitcnt lgkmcnt(0)
	v_add_f32_e32 v208, v208, v212
	v_add_f32_e32 v209, v209, v213
	v_add_f32_e32 v210, v210, v214
	v_add_f32_e32 v211, v211, v215
	ds_bpermute_b32 v212, v46, v208
	ds_bpermute_b32 v213, v46, v209
	ds_bpermute_b32 v214, v46, v210
	ds_bpermute_b32 v215, v46, v211
	s_waitcnt lgkmcnt(0)
	v_add_f32_e32 v208, v208, v212
	v_add_f32_e32 v209, v209, v213
	v_add_f32_e32 v210, v210, v214
	v_add_f32_e32 v211, v211, v215
	v_fmamk_f32 v208, v208, 0x3a800000, v230
	v_cmp_gt_f32_e32 vcc, s92, v208
	v_mul_f32_e32 v212, 0x4b800000, v208
	s_nop 1
	v_cndmask_b32_e32 v208, v208, v212, vcc
	v_rsq_f32_e32 v208, v208
	s_nop 0
	v_mul_f32_e32 v212, 0x45800000, v208
	v_cndmask_b32_e32 v208, v208, v212, vcc
	v_fmamk_f32 v209, v209, 0x3a800000, v230
	v_cmp_gt_f32_e32 vcc, s92, v209
	v_mul_f32_e32 v212, 0x4b800000, v209
	s_nop 1
	v_cndmask_b32_e32 v209, v209, v212, vcc
	v_rsq_f32_e32 v209, v209
	s_nop 0
	v_mul_f32_e32 v212, 0x45800000, v209
	v_cndmask_b32_e32 v209, v209, v212, vcc
	v_fmamk_f32 v210, v210, 0x3a800000, v230
	v_cmp_gt_f32_e32 vcc, s92, v210
	v_mul_f32_e32 v212, 0x4b800000, v210
	s_nop 1
	v_cndmask_b32_e32 v210, v210, v212, vcc
	v_rsq_f32_e32 v210, v210
	s_nop 0
	v_mul_f32_e32 v212, 0x45800000, v210
	v_cndmask_b32_e32 v210, v210, v212, vcc
	v_fmamk_f32 v211, v211, 0x3a800000, v230
	v_cmp_gt_f32_e32 vcc, s92, v211
	v_mul_f32_e32 v212, 0x4b800000, v211
	s_nop 1
	v_cndmask_b32_e32 v211, v211, v212, vcc
	v_rsq_f32_e32 v211, v211
	s_nop 0
	v_mul_f32_e32 v212, 0x45800000, v211
	v_cndmask_b32_e32 v211, v211, v212, vcc
	s_lshl_b32 s14, s2, 11
	s_mov_b32 s15, 0
	s_waitcnt vmcnt(8)
	v_lshl_add_u64 v[62:63], v[24:25], 0, s[14:15]
	v_mul_f32_e32 v64, v64, v208
	v_mul_f32_e32 v64, v128, v64
	v_add_f32_e32 v216, 1.0, v144
	v_fma_f32 v64, v216, v64, v160
	v_mul_f32_e32 v65, v65, v208
	v_mul_f32_e32 v65, v129, v65
	v_add_f32_e32 v217, 1.0, v145
	v_fma_f32 v65, v217, v65, v161
	v_mul_f32_e32 v66, v66, v208
	v_mul_f32_e32 v66, v130, v66
	v_add_f32_e32 v218, 1.0, v146
	v_fma_f32 v66, v218, v66, v162
	v_mul_f32_e32 v67, v67, v208
	v_mul_f32_e32 v67, v131, v67
	v_add_f32_e32 v219, 1.0, v147
	v_fma_f32 v67, v219, v67, v163
	v_bfe_u32 v220, v64, 16, 1
	v_add3_u32 v64, v64, v220, s89
	v_bfe_u32 v221, v65, 16, 1
	v_add3_u32 v65, v65, v221, s89
	v_bfe_u32 v222, v66, 16, 1
	v_add3_u32 v66, v66, v222, s89
	v_bfe_u32 v223, v67, 16, 1
	v_add3_u32 v67, v67, v223, s89
	v_perm_b32 v64, v65, v64, s8
	v_perm_b32 v65, v67, v66, s8
	global_store_dwordx2 v[62:63], v[64:65], off
	v_mul_f32_e32 v68, v68, v208
	v_mul_f32_e32 v68, v132, v68
	v_add_f32_e32 v216, 1.0, v148
	v_fma_f32 v68, v216, v68, v164
	v_mul_f32_e32 v69, v69, v208
	v_mul_f32_e32 v69, v133, v69
	v_add_f32_e32 v217, 1.0, v149
	v_fma_f32 v69, v217, v69, v165
	v_mul_f32_e32 v70, v70, v208
	v_mul_f32_e32 v70, v134, v70
	v_add_f32_e32 v218, 1.0, v150
	v_fma_f32 v70, v218, v70, v166
	v_mul_f32_e32 v71, v71, v208
	v_mul_f32_e32 v71, v135, v71
	v_add_f32_e32 v219, 1.0, v151
	v_fma_f32 v71, v219, v71, v167
	v_bfe_u32 v220, v68, 16, 1
	v_add3_u32 v68, v68, v220, s89
	v_bfe_u32 v221, v69, 16, 1
	v_add3_u32 v69, v69, v221, s89
	v_bfe_u32 v222, v70, 16, 1
	v_add3_u32 v70, v70, v222, s89
	v_bfe_u32 v223, v71, 16, 1
	v_add3_u32 v71, v71, v223, s89
	v_perm_b32 v68, v69, v68, s8
	v_perm_b32 v69, v71, v70, s8
	global_store_dwordx2 v[62:63], v[68:69], off offset:512
	v_mul_f32_e32 v72, v72, v208
	v_mul_f32_e32 v72, v136, v72
	v_add_f32_e32 v216, 1.0, v152
	v_fma_f32 v72, v216, v72, v168
	v_mul_f32_e32 v73, v73, v208
	v_mul_f32_e32 v73, v137, v73
	v_add_f32_e32 v217, 1.0, v153
	v_fma_f32 v73, v217, v73, v169
	v_mul_f32_e32 v74, v74, v208
	v_mul_f32_e32 v74, v138, v74
	v_add_f32_e32 v218, 1.0, v154
	v_fma_f32 v74, v218, v74, v170
	v_mul_f32_e32 v75, v75, v208
	v_mul_f32_e32 v75, v139, v75
	v_add_f32_e32 v219, 1.0, v155
	v_fma_f32 v75, v219, v75, v171
	v_bfe_u32 v220, v72, 16, 1
	v_add3_u32 v72, v72, v220, s89
	v_bfe_u32 v221, v73, 16, 1
	v_add3_u32 v73, v73, v221, s89
	v_bfe_u32 v222, v74, 16, 1
	v_add3_u32 v74, v74, v222, s89
	v_bfe_u32 v223, v75, 16, 1
	v_add3_u32 v75, v75, v223, s89
	v_perm_b32 v72, v73, v72, s8
	v_perm_b32 v73, v75, v74, s8
	global_store_dwordx2 v[62:63], v[72:73], off offset:1024
	v_mul_f32_e32 v76, v76, v208
	v_mul_f32_e32 v76, v140, v76
	v_add_f32_e32 v216, 1.0, v156
	v_fma_f32 v76, v216, v76, v172
	v_mul_f32_e32 v77, v77, v208
	v_mul_f32_e32 v77, v141, v77
	v_add_f32_e32 v217, 1.0, v157
	v_fma_f32 v77, v217, v77, v173
	v_mul_f32_e32 v78, v78, v208
	v_mul_f32_e32 v78, v142, v78
	v_add_f32_e32 v218, 1.0, v158
	v_fma_f32 v78, v218, v78, v174
	v_mul_f32_e32 v79, v79, v208
	v_mul_f32_e32 v79, v143, v79
	v_add_f32_e32 v219, 1.0, v159
	v_fma_f32 v79, v219, v79, v175
	v_bfe_u32 v220, v76, 16, 1
	v_add3_u32 v76, v76, v220, s89
	v_bfe_u32 v221, v77, 16, 1
	v_add3_u32 v77, v77, v221, s89
	v_bfe_u32 v222, v78, 16, 1
	v_add3_u32 v78, v78, v222, s89
	v_bfe_u32 v223, v79, 16, 1
	v_add3_u32 v79, v79, v223, s89
	v_perm_b32 v76, v77, v76, s8
	v_perm_b32 v77, v79, v78, s8
	global_store_dwordx2 v[62:63], v[76:77], off offset:1536
	s_add_u32 s3, s2, 0x1000
	s_sub_u32 s5, s3, 2048
	s_lshr_b32 s5, s5, 11
	s_cmp_lt_u32 s3, 4096
	s_cselect_b32 s5, 0, s5
	s_mul_i32 s5, s5, 0x6000
	s_add_u32 s18, s10, s5
	s_addc_u32 s19, s11, 0
	s_add_u32 s20, s18, 0x3000
	s_addc_u32 s21, s19, 0
	s_add_u32 s18, s18, 0x4000
	s_addc_u32 s19, s19, 0
	global_load_dwordx4 v[144:147], v26, s[18:19]
	global_load_dwordx4 v[148:151], v26, s[18:19] offset:1024
	global_load_dwordx4 v[152:155], v26, s[18:19] offset:2048
	global_load_dwordx4 v[156:159], v26, s[18:19] offset:3072
	global_load_dwordx4 v[160:163], v26, s[20:21]
	global_load_dwordx4 v[164:167], v26, s[20:21] offset:1024
	global_load_dwordx4 v[168:171], v26, s[20:21] offset:2048
	global_load_dwordx4 v[172:175], v26, s[20:21] offset:3072
	s_add_u32 s14, s14, 0x400000
	s_waitcnt vmcnt(12)
	v_lshl_add_u64 v[62:63], v[24:25], 0, s[14:15]
	v_mul_f32_e32 v80, v80, v209
	v_mul_f32_e32 v80, v128, v80
	v_add_f32_e32 v216, 1.0, v176
	v_fma_f32 v80, v216, v80, v192
	v_mul_f32_e32 v81, v81, v209
	v_mul_f32_e32 v81, v129, v81
	v_add_f32_e32 v217, 1.0, v177
	v_fma_f32 v81, v217, v81, v193
	v_mul_f32_e32 v82, v82, v209
	v_mul_f32_e32 v82, v130, v82
	v_add_f32_e32 v218, 1.0, v178
	v_fma_f32 v82, v218, v82, v194
	v_mul_f32_e32 v83, v83, v209
	v_mul_f32_e32 v83, v131, v83
	v_add_f32_e32 v219, 1.0, v179
	v_fma_f32 v83, v219, v83, v195
	v_bfe_u32 v220, v80, 16, 1
	v_add3_u32 v80, v80, v220, s89
	v_bfe_u32 v221, v81, 16, 1
	v_add3_u32 v81, v81, v221, s89
	v_bfe_u32 v222, v82, 16, 1
	v_add3_u32 v82, v82, v222, s89
	v_bfe_u32 v223, v83, 16, 1
	v_add3_u32 v83, v83, v223, s89
	v_perm_b32 v80, v81, v80, s8
	v_perm_b32 v81, v83, v82, s8
	global_store_dwordx2 v[62:63], v[80:81], off
	v_mul_f32_e32 v84, v84, v209
	v_mul_f32_e32 v84, v132, v84
	v_add_f32_e32 v216, 1.0, v180
	v_fma_f32 v84, v216, v84, v196
	v_mul_f32_e32 v85, v85, v209
	v_mul_f32_e32 v85, v133, v85
	v_add_f32_e32 v217, 1.0, v181
	v_fma_f32 v85, v217, v85, v197
	v_mul_f32_e32 v86, v86, v209
	v_mul_f32_e32 v86, v134, v86
	v_add_f32_e32 v218, 1.0, v182
	v_fma_f32 v86, v218, v86, v198
	v_mul_f32_e32 v87, v87, v209
	v_mul_f32_e32 v87, v135, v87
	v_add_f32_e32 v219, 1.0, v183
	v_fma_f32 v87, v219, v87, v199
	v_bfe_u32 v220, v84, 16, 1
	v_add3_u32 v84, v84, v220, s89
	v_bfe_u32 v221, v85, 16, 1
	v_add3_u32 v85, v85, v221, s89
	v_bfe_u32 v222, v86, 16, 1
	v_add3_u32 v86, v86, v222, s89
	v_bfe_u32 v223, v87, 16, 1
	v_add3_u32 v87, v87, v223, s89
	v_perm_b32 v84, v85, v84, s8
	v_perm_b32 v85, v87, v86, s8
	global_store_dwordx2 v[62:63], v[84:85], off offset:512
	v_mul_f32_e32 v88, v88, v209
	v_mul_f32_e32 v88, v136, v88
	v_add_f32_e32 v216, 1.0, v184
	v_fma_f32 v88, v216, v88, v200
	v_mul_f32_e32 v89, v89, v209
	v_mul_f32_e32 v89, v137, v89
	v_add_f32_e32 v217, 1.0, v185
	v_fma_f32 v89, v217, v89, v201
	v_mul_f32_e32 v90, v90, v209
	v_mul_f32_e32 v90, v138, v90
	v_add_f32_e32 v218, 1.0, v186
	v_fma_f32 v90, v218, v90, v202
	v_mul_f32_e32 v91, v91, v209
	v_mul_f32_e32 v91, v139, v91
	v_add_f32_e32 v219, 1.0, v187
	v_fma_f32 v91, v219, v91, v203
	v_bfe_u32 v220, v88, 16, 1
	v_add3_u32 v88, v88, v220, s89
	v_bfe_u32 v221, v89, 16, 1
	v_add3_u32 v89, v89, v221, s89
	v_bfe_u32 v222, v90, 16, 1
	v_add3_u32 v90, v90, v222, s89
	v_bfe_u32 v223, v91, 16, 1
	v_add3_u32 v91, v91, v223, s89
	v_perm_b32 v88, v89, v88, s8
	v_perm_b32 v89, v91, v90, s8
	global_store_dwordx2 v[62:63], v[88:89], off offset:1024
	v_mul_f32_e32 v92, v92, v209
	v_mul_f32_e32 v92, v140, v92
	v_add_f32_e32 v216, 1.0, v188
	v_fma_f32 v92, v216, v92, v204
	v_mul_f32_e32 v93, v93, v209
	v_mul_f32_e32 v93, v141, v93
	v_add_f32_e32 v217, 1.0, v189
	v_fma_f32 v93, v217, v93, v205
	v_mul_f32_e32 v94, v94, v209
	v_mul_f32_e32 v94, v142, v94
	v_add_f32_e32 v218, 1.0, v190
	v_fma_f32 v94, v218, v94, v206
	v_mul_f32_e32 v95, v95, v209
	v_mul_f32_e32 v95, v143, v95
	v_add_f32_e32 v219, 1.0, v191
	v_fma_f32 v95, v219, v95, v207
	v_bfe_u32 v220, v92, 16, 1
	v_add3_u32 v92, v92, v220, s89
	v_bfe_u32 v221, v93, 16, 1
	v_add3_u32 v93, v93, v221, s89
	v_bfe_u32 v222, v94, 16, 1
	v_add3_u32 v94, v94, v222, s89
	v_bfe_u32 v223, v95, 16, 1
	v_add3_u32 v95, v95, v223, s89
	v_perm_b32 v92, v93, v92, s8
	v_perm_b32 v93, v95, v94, s8
	global_store_dwordx2 v[62:63], v[92:93], off offset:1536
	s_add_u32 s3, s2, 0x1800
	s_sub_u32 s5, s3, 2048
	s_lshr_b32 s5, s5, 11
	s_cmp_lt_u32 s3, 4096
	s_cselect_b32 s5, 0, s5
	s_mul_i32 s5, s5, 0x6000
	s_add_u32 s18, s10, s5
	s_addc_u32 s19, s11, 0
	s_add_u32 s20, s18, 0x3000
	s_addc_u32 s21, s19, 0
	s_add_u32 s18, s18, 0x4000
	s_addc_u32 s19, s19, 0
	global_load_dwordx4 v[176:179], v26, s[18:19]
	global_load_dwordx4 v[180:183], v26, s[18:19] offset:1024
	global_load_dwordx4 v[184:187], v26, s[18:19] offset:2048
	global_load_dwordx4 v[188:191], v26, s[18:19] offset:3072
	global_load_dwordx4 v[192:195], v26, s[20:21]
	global_load_dwordx4 v[196:199], v26, s[20:21] offset:1024
	global_load_dwordx4 v[200:203], v26, s[20:21] offset:2048
	global_load_dwordx4 v[204:207], v26, s[20:21] offset:3072
	s_add_u32 s14, s14, 0x400000
	s_waitcnt vmcnt(12)
	v_lshl_add_u64 v[62:63], v[24:25], 0, s[14:15]
	v_mul_f32_e32 v96, v96, v210
	v_mul_f32_e32 v96, v128, v96
	v_add_f32_e32 v216, 1.0, v144
	v_fma_f32 v96, v216, v96, v160
	v_mul_f32_e32 v97, v97, v210
	v_mul_f32_e32 v97, v129, v97
	v_add_f32_e32 v217, 1.0, v145
	v_fma_f32 v97, v217, v97, v161
	v_mul_f32_e32 v98, v98, v210
	v_mul_f32_e32 v98, v130, v98
	v_add_f32_e32 v218, 1.0, v146
	v_fma_f32 v98, v218, v98, v162
	v_mul_f32_e32 v99, v99, v210
	v_mul_f32_e32 v99, v131, v99
	v_add_f32_e32 v219, 1.0, v147
	v_fma_f32 v99, v219, v99, v163
	v_bfe_u32 v220, v96, 16, 1
	v_add3_u32 v96, v96, v220, s89
	v_bfe_u32 v221, v97, 16, 1
	v_add3_u32 v97, v97, v221, s89
	v_bfe_u32 v222, v98, 16, 1
	v_add3_u32 v98, v98, v222, s89
	v_bfe_u32 v223, v99, 16, 1
	v_add3_u32 v99, v99, v223, s89
	v_perm_b32 v96, v97, v96, s8
	v_perm_b32 v97, v99, v98, s8
	global_store_dwordx2 v[62:63], v[96:97], off
	v_mul_f32_e32 v100, v100, v210
	v_mul_f32_e32 v100, v132, v100
	v_add_f32_e32 v216, 1.0, v148
	v_fma_f32 v100, v216, v100, v164
	v_mul_f32_e32 v101, v101, v210
	v_mul_f32_e32 v101, v133, v101
	v_add_f32_e32 v217, 1.0, v149
	v_fma_f32 v101, v217, v101, v165
	v_mul_f32_e32 v102, v102, v210
	v_mul_f32_e32 v102, v134, v102
	v_add_f32_e32 v218, 1.0, v150
	v_fma_f32 v102, v218, v102, v166
	v_mul_f32_e32 v103, v103, v210
	v_mul_f32_e32 v103, v135, v103
	v_add_f32_e32 v219, 1.0, v151
	v_fma_f32 v103, v219, v103, v167
	v_bfe_u32 v220, v100, 16, 1
	v_add3_u32 v100, v100, v220, s89
	v_bfe_u32 v221, v101, 16, 1
	v_add3_u32 v101, v101, v221, s89
	v_bfe_u32 v222, v102, 16, 1
	v_add3_u32 v102, v102, v222, s89
	v_bfe_u32 v223, v103, 16, 1
	v_add3_u32 v103, v103, v223, s89
	v_perm_b32 v100, v101, v100, s8
	v_perm_b32 v101, v103, v102, s8
	global_store_dwordx2 v[62:63], v[100:101], off offset:512
	v_mul_f32_e32 v104, v104, v210
	v_mul_f32_e32 v104, v136, v104
	v_add_f32_e32 v216, 1.0, v152
	v_fma_f32 v104, v216, v104, v168
	v_mul_f32_e32 v105, v105, v210
	v_mul_f32_e32 v105, v137, v105
	v_add_f32_e32 v217, 1.0, v153
	v_fma_f32 v105, v217, v105, v169
	v_mul_f32_e32 v106, v106, v210
	v_mul_f32_e32 v106, v138, v106
	v_add_f32_e32 v218, 1.0, v154
	v_fma_f32 v106, v218, v106, v170
	v_mul_f32_e32 v107, v107, v210
	v_mul_f32_e32 v107, v139, v107
	v_add_f32_e32 v219, 1.0, v155
	v_fma_f32 v107, v219, v107, v171
	v_bfe_u32 v220, v104, 16, 1
	v_add3_u32 v104, v104, v220, s89
	v_bfe_u32 v221, v105, 16, 1
	v_add3_u32 v105, v105, v221, s89
	v_bfe_u32 v222, v106, 16, 1
	v_add3_u32 v106, v106, v222, s89
	v_bfe_u32 v223, v107, 16, 1
	v_add3_u32 v107, v107, v223, s89
	v_perm_b32 v104, v105, v104, s8
	v_perm_b32 v105, v107, v106, s8
	global_store_dwordx2 v[62:63], v[104:105], off offset:1024
	v_mul_f32_e32 v108, v108, v210
	v_mul_f32_e32 v108, v140, v108
	v_add_f32_e32 v216, 1.0, v156
	v_fma_f32 v108, v216, v108, v172
	v_mul_f32_e32 v109, v109, v210
	v_mul_f32_e32 v109, v141, v109
	v_add_f32_e32 v217, 1.0, v157
	v_fma_f32 v109, v217, v109, v173
	v_mul_f32_e32 v110, v110, v210
	v_mul_f32_e32 v110, v142, v110
	v_add_f32_e32 v218, 1.0, v158
	v_fma_f32 v110, v218, v110, v174
	v_mul_f32_e32 v111, v111, v210
	v_mul_f32_e32 v111, v143, v111
	v_add_f32_e32 v219, 1.0, v159
	v_fma_f32 v111, v219, v111, v175
	v_bfe_u32 v220, v108, 16, 1
	v_add3_u32 v108, v108, v220, s89
	v_bfe_u32 v221, v109, 16, 1
	v_add3_u32 v109, v109, v221, s89
	v_bfe_u32 v222, v110, 16, 1
	v_add3_u32 v110, v110, v222, s89
	v_bfe_u32 v223, v111, 16, 1
	v_add3_u32 v111, v111, v223, s89
	v_perm_b32 v108, v109, v108, s8
	v_perm_b32 v109, v111, v110, s8
	global_store_dwordx2 v[62:63], v[108:109], off offset:1536
	s_add_u32 s14, s14, 0x400000
	s_waitcnt vmcnt(4)
	v_lshl_add_u64 v[62:63], v[24:25], 0, s[14:15]
	v_mul_f32_e32 v112, v112, v211
	v_mul_f32_e32 v112, v128, v112
	v_add_f32_e32 v216, 1.0, v176
	v_fma_f32 v112, v216, v112, v192
	v_mul_f32_e32 v113, v113, v211
	v_mul_f32_e32 v113, v129, v113
	v_add_f32_e32 v217, 1.0, v177
	v_fma_f32 v113, v217, v113, v193
	v_mul_f32_e32 v114, v114, v211
	v_mul_f32_e32 v114, v130, v114
	v_add_f32_e32 v218, 1.0, v178
	v_fma_f32 v114, v218, v114, v194
	v_mul_f32_e32 v115, v115, v211
	v_mul_f32_e32 v115, v131, v115
	v_add_f32_e32 v219, 1.0, v179
	v_fma_f32 v115, v219, v115, v195
	v_bfe_u32 v220, v112, 16, 1
	v_add3_u32 v112, v112, v220, s89
	v_bfe_u32 v221, v113, 16, 1
	v_add3_u32 v113, v113, v221, s89
	v_bfe_u32 v222, v114, 16, 1
	v_add3_u32 v114, v114, v222, s89
	v_bfe_u32 v223, v115, 16, 1
	v_add3_u32 v115, v115, v223, s89
	v_perm_b32 v112, v113, v112, s8
	v_perm_b32 v113, v115, v114, s8
	global_store_dwordx2 v[62:63], v[112:113], off
	v_mul_f32_e32 v116, v116, v211
	v_mul_f32_e32 v116, v132, v116
	v_add_f32_e32 v216, 1.0, v180
	v_fma_f32 v116, v216, v116, v196
	v_mul_f32_e32 v117, v117, v211
	v_mul_f32_e32 v117, v133, v117
	v_add_f32_e32 v217, 1.0, v181
	v_fma_f32 v117, v217, v117, v197
	v_mul_f32_e32 v118, v118, v211
	v_mul_f32_e32 v118, v134, v118
	v_add_f32_e32 v218, 1.0, v182
	v_fma_f32 v118, v218, v118, v198
	v_mul_f32_e32 v119, v119, v211
	v_mul_f32_e32 v119, v135, v119
	v_add_f32_e32 v219, 1.0, v183
	v_fma_f32 v119, v219, v119, v199
	v_bfe_u32 v220, v116, 16, 1
	v_add3_u32 v116, v116, v220, s89
	v_bfe_u32 v221, v117, 16, 1
	v_add3_u32 v117, v117, v221, s89
	v_bfe_u32 v222, v118, 16, 1
	v_add3_u32 v118, v118, v222, s89
	v_bfe_u32 v223, v119, 16, 1
	v_add3_u32 v119, v119, v223, s89
	v_perm_b32 v116, v117, v116, s8
	v_perm_b32 v117, v119, v118, s8
	global_store_dwordx2 v[62:63], v[116:117], off offset:512
	v_mul_f32_e32 v120, v120, v211
	v_mul_f32_e32 v120, v136, v120
	v_add_f32_e32 v216, 1.0, v184
	v_fma_f32 v120, v216, v120, v200
	v_mul_f32_e32 v121, v121, v211
	v_mul_f32_e32 v121, v137, v121
	v_add_f32_e32 v217, 1.0, v185
	v_fma_f32 v121, v217, v121, v201
	v_mul_f32_e32 v122, v122, v211
	v_mul_f32_e32 v122, v138, v122
	v_add_f32_e32 v218, 1.0, v186
	v_fma_f32 v122, v218, v122, v202
	v_mul_f32_e32 v123, v123, v211
	v_mul_f32_e32 v123, v139, v123
	v_add_f32_e32 v219, 1.0, v187
	v_fma_f32 v123, v219, v123, v203
	v_bfe_u32 v220, v120, 16, 1
	v_add3_u32 v120, v120, v220, s89
	v_bfe_u32 v221, v121, 16, 1
	v_add3_u32 v121, v121, v221, s89
	v_bfe_u32 v222, v122, 16, 1
	v_add3_u32 v122, v122, v222, s89
	v_bfe_u32 v223, v123, 16, 1
	v_add3_u32 v123, v123, v223, s89
	v_perm_b32 v120, v121, v120, s8
	v_perm_b32 v121, v123, v122, s8
	global_store_dwordx2 v[62:63], v[120:121], off offset:1024
	v_mul_f32_e32 v124, v124, v211
	v_mul_f32_e32 v124, v140, v124
	v_add_f32_e32 v216, 1.0, v188
	v_fma_f32 v124, v216, v124, v204
	v_mul_f32_e32 v125, v125, v211
	v_mul_f32_e32 v125, v141, v125
	v_add_f32_e32 v217, 1.0, v189
	v_fma_f32 v125, v217, v125, v205
	v_mul_f32_e32 v126, v126, v211
	v_mul_f32_e32 v126, v142, v126
	v_add_f32_e32 v218, 1.0, v190
	v_fma_f32 v126, v218, v126, v206
	v_mul_f32_e32 v127, v127, v211
	v_mul_f32_e32 v127, v143, v127
	v_add_f32_e32 v219, 1.0, v191
	v_fma_f32 v127, v219, v127, v207
	v_bfe_u32 v220, v124, 16, 1
	v_add3_u32 v124, v124, v220, s89
	v_bfe_u32 v221, v125, 16, 1
	v_add3_u32 v125, v125, v221, s89
	v_bfe_u32 v222, v126, 16, 1
	v_add3_u32 v126, v126, v222, s89
	v_bfe_u32 v223, v127, 16, 1
	v_add3_u32 v127, v127, v223, s89
	v_perm_b32 v124, v125, v124, s8
	v_perm_b32 v125, v127, v126, s8
	global_store_dwordx2 v[62:63], v[124:125], off offset:1536
	s_branch .LBB0_2129
